# nt hint on the P1 Hyena-filter (GR) short stores, on top of the streaming-load nt hints
# baseline (speedup 1.0000x reference)
.LBB0_277:
	s_ashr_i32 s0, s82, 31
	s_lshr_b32 s0, s0, 27
	s_add_i32 s0, s82, s0
	s_ashr_i32 s4, s0, 5
	s_andn2_b32 s0, s0, 31
	s_ashr_i32 s5, s4, 31
	s_sub_i32 s0, s82, s0
	s_lshl_b64 s[8:9], s[4:5], 15
	s_add_u32 s8, s3, s8
	s_addc_u32 s9, s12, s9
	s_ashr_i32 s1, s0, 31
	s_lshl_b64 s[10:11], s[0:1], 14
	s_add_u32 s10, s13, s10
	s_getreg_b32 s1, hwreg(HW_REG_HW_ID, 0, 6)
	s_addc_u32 s11, s14, s11
	s_lshl_b32 s1, s1, 2
	s_and_b32 s1, s1, 0xfc
	s_add_i32 s1, s1, 0
	s_add_i32 s1, s1, 0x256c0
	v_mov_b32_e32 v0, s1
	ds_read_b32 v0, v0
	v_mbcnt_lo_u32_b32 v8, -1, 0
	v_mbcnt_hi_u32_b32 v8, -1, v8
	s_lshl_b32 s0, s0, 7
	v_and_b32_e32 v88, 31, v8
	v_bfe_u32 v70, v8, 5, 1
	s_waitcnt lgkmcnt(0)
	v_readfirstlane_b32 s1, v0
	v_lshlrev_b32_e32 v128, 2, v70
	s_nop 0
	v_lshl_add_u32 v9, s1, 6, v8
	v_ashrrev_i32_e32 v0, 3, v9
	v_ashrrev_i32_e32 v1, 31, v0
	v_lshlrev_b64 v[2:3], 7, v[0:1]
	v_lshlrev_b32_e32 v1, 4, v8
	v_lshl_add_u64 v[4:5], s[8:9], 0, v[2:3]
	v_and_b32_e32 v64, 0x70, v1
	v_lshl_add_u64 v[4:5], v[4:5], 0, v[64:65]
	v_add_co_u32_e32 v6, vcc, s24, v4
	v_lshl_add_u64 v[2:3], s[10:11], 0, v[2:3]
	s_nop 0
	v_addc_co_u32_e32 v7, vcc, 0, v5, vcc
	global_load_dwordx4 v[72:75], v[4:5], off
	global_load_dwordx4 v[76:79], v[6:7], off
	v_add_co_u32_e32 v6, vcc, s25, v4
	v_lshl_add_u64 v[2:3], v[2:3], 0, v[64:65]
	s_nop 0
	v_addc_co_u32_e32 v7, vcc, 0, v5, vcc
	v_add_co_u32_e32 v4, vcc, s26, v4
	v_ashrrev_i32_e32 v1, 1, v9
	s_nop 0
	v_addc_co_u32_e32 v5, vcc, 0, v5, vcc
	global_load_dwordx4 v[80:83], v[6:7], off
	global_load_dwordx4 v[84:87], v[4:5], off
	global_load_dwordx4 v[92:95], v[2:3], off
	v_add_co_u32_e32 v2, vcc, s24, v2
	v_and_b32_e32 v71, 0xffffffc0, v1
	s_nop 0
	v_addc_co_u32_e32 v3, vcc, 0, v3, vcc
	global_load_dwordx4 v[96:99], v[2:3], off
	v_mul_lo_u32 v0, v0, s15
	v_or_b32_e32 v1, v71, v88
	v_lshlrev_b32_e32 v4, 4, v70
	v_add3_u32 v64, v0, v64, 0
	v_mul_lo_u32 v0, v1, s15
	v_add3_u32 v91, v0, v4, 0
	v_and_b32_e32 v89, 64, v9
	v_or_b32_e32 v5, v89, v88
	v_mul_u32_u24_e32 v5, 0x90, v5
	v_add3_u32 v116, v4, v5, 0
	v_lshl_add_u32 v129, s4, 8, v71
	s_waitcnt vmcnt(5)
	ds_write_b128 v64, v[72:75]
	s_waitcnt vmcnt(1)
	ds_write_b128 v64, v[92:95] offset:36864
	ds_write_b128 v64, v[76:79] offset:9216
	ds_write_b128 v64, v[80:83] offset:18432
	ds_write_b128 v64, v[84:87] offset:27648
	s_waitcnt vmcnt(0)
	ds_write_b128 v64, v[96:99] offset:46080
	s_waitcnt lgkmcnt(0)
	s_barrier
	ds_read_b128 v[0:3], v91
	ds_read_b128 v[4:7], v116 offset:36864
	ds_read_b128 v[66:69], v91 offset:32
	ds_read_b128 v[100:103], v116 offset:36896
	ds_read_b128 v[8:11], v116 offset:41472
	ds_read_b128 v[104:107], v116 offset:41504
	s_waitcnt lgkmcnt(4)
	v_mfma_f32_32x32x16_bf16 v[48:63], v[0:3], v[4:7], 0
	s_waitcnt lgkmcnt(1)
	v_mfma_f32_32x32x16_bf16 v[32:47], v[0:3], v[8:11], 0
	ds_read_b128 v[0:3], v91 offset:4608
	ds_read_b128 v[108:111], v91 offset:4640
	s_waitcnt lgkmcnt(1)
	v_mfma_f32_32x32x16_bf16 v[16:31], v[0:3], v[4:7], 0
	v_mfma_f32_32x32x16_bf16 v[0:15], v[0:3], v[8:11], 0
	v_mfma_f32_32x32x16_bf16 v[48:63], v[66:69], v[100:103], v[48:63]
	v_mfma_f32_32x32x16_bf16 v[32:47], v[66:69], v[104:107], v[32:47]
	s_waitcnt lgkmcnt(0)
	v_mfma_f32_32x32x16_bf16 v[16:31], v[108:111], v[100:103], v[16:31]
	v_mfma_f32_32x32x16_bf16 v[0:15], v[108:111], v[104:107], v[0:15]
	ds_read_b128 v[66:69], v91 offset:64
	ds_read_b128 v[100:103], v116 offset:36928
	ds_read_b128 v[104:107], v91 offset:96
	ds_read_b128 v[108:111], v116 offset:36960
	ds_read_b128 v[112:115], v116 offset:41536
	ds_read_b128 v[116:119], v116 offset:41568
	ds_read_b128 v[120:123], v91 offset:4672
	ds_read_b128 v[124:127], v91 offset:4704
	ds_write_b128 v64, v[72:75] offset:55296
	ds_write_b128 v64, v[76:79] offset:64512
	v_bitop3_b32 v72, v129, s27, v128 bitop3:0xc8
	v_cvt_f32_u32_e32 v74, v72
	s_waitcnt lgkmcnt(8)
	v_mfma_f32_32x32x16_bf16 v[48:63], v[66:69], v[100:103], v[48:63]
	v_and_b32_e32 v73, 0x400, v129
	s_waitcnt lgkmcnt(5)
	v_mfma_f32_32x32x16_bf16 v[32:47], v[66:69], v[112:115], v[32:47]
	v_or_b32_e32 v68, v129, v128
	v_ashrrev_i32_e32 v69, 31, v68
	v_add_u32_e32 v66, 0xd800, v64
	v_lshl_add_u64 v[70:71], v[68:69], 2, s[50:51]
	v_add_u32_e32 v67, 0x16800, v64
	ds_write_b128 v66, v[80:83] offset:18432
	ds_write_b128 v66, v[84:87] offset:27648
	ds_write_b128 v67, v[92:95]
	ds_write_b128 v67, v[96:99] offset:9216
	s_waitcnt lgkmcnt(0)
	s_barrier
	global_load_dword v200, v[70:71], off
	global_load_dword v201, v[70:71], off offset:4
	global_load_dword v202, v[70:71], off offset:8
	global_load_dword v203, v[70:71], off offset:12
	global_load_dword v204, v[70:71], off offset:32
	global_load_dword v205, v[70:71], off offset:36
	global_load_dword v206, v[70:71], off offset:40
	global_load_dword v207, v[70:71], off offset:44
	global_load_dword v208, v[70:71], off offset:64
	global_load_dword v209, v[70:71], off offset:68
	global_load_dword v210, v[70:71], off offset:72
	global_load_dword v211, v[70:71], off offset:76
	global_load_dword v212, v[70:71], off offset:96
	global_load_dword v213, v[70:71], off offset:100
	global_load_dword v214, v[70:71], off offset:104
	global_load_dword v215, v[70:71], off offset:108
	global_load_dword v216, v[70:71], off offset:128
	global_load_dword v217, v[70:71], off offset:132
	global_load_dword v218, v[70:71], off offset:136
	global_load_dword v219, v[70:71], off offset:140
	global_load_dword v220, v[70:71], off offset:160
	global_load_dword v221, v[70:71], off offset:164
	global_load_dword v222, v[70:71], off offset:168
	global_load_dword v223, v[70:71], off offset:172
	global_load_dword v224, v[70:71], off offset:192
	global_load_dword v225, v[70:71], off offset:196
	global_load_dword v226, v[70:71], off offset:200
	global_load_dword v227, v[70:71], off offset:204
	global_load_dword v228, v[70:71], off offset:224
	global_load_dword v229, v[70:71], off offset:228
	global_load_dword v230, v[70:71], off offset:232
	global_load_dword v231, v[70:71], off offset:236
	v_mfma_f32_32x32x16_bf16 v[16:31], v[120:123], v[100:103], v[16:31]
	v_or3_b32 v66, v88, s0, v89
	v_cvt_f32_i32_e32 v64, v66
	v_fmamk_f32 v94, v74, 0xbc44ade8, v90
	v_ashrrev_i32_e32 v69, 1, v129
	v_and_b32_e32 v69, 0xfffffc00, v69
	v_mul_f32_e32 v91, 0xb9800801, v64
	v_mul_f32_e64 v64, v91, |v94|
	v_mfma_f32_32x32x16_bf16 v[0:15], v[120:123], v[112:115], v[0:15]
	v_mul_f32_e32 v64, 0x3fb8aa3b, v64
	v_exp_f32_e32 v64, v64
	v_or_b32_e32 v72, v69, v72
	v_cmp_ne_u32_e64 s[0:1], 0, v73
	v_ashrrev_i32_e32 v73, 31, v72
	v_lshlrev_b64 v[72:73], 14, v[72:73]
	v_cmp_ne_u32_e64 s[4:5], 0, v66
	v_mfma_f32_32x32x16_bf16 v[48:63], v[104:107], v[108:111], v[48:63]
	v_ashrrev_i32_e32 v67, 31, v66
	v_lshl_add_u64 v[72:73], s[6:7], 0, v[72:73]
	v_mfma_f32_32x32x16_bf16 v[32:47], v[104:107], v[116:119], v[32:47]
	s_waitcnt vmcnt(0)
	s_nop 7
	v_add_f32_e32 v48, v48, v200
	v_mfma_f32_32x32x16_bf16 v[16:31], v[124:127], v[108:111], v[16:31]
	v_mul_f32_e32 v48, v64, v48
	v_mfma_f32_32x32x16_bf16 v[0:15], v[124:127], v[116:119], v[0:15]
	s_and_saveexec_b64 s[8:9], s[0:1]
	s_xor_b64 s[8:9], exec, s[8:9]
	s_cbranch_execz .LBB0_283
	s_and_saveexec_b64 s[10:11], s[4:5]
	s_xor_b64 s[10:11], exec, s[10:11]
	s_cbranch_execz .LBB0_280
	v_lshl_add_u64 v[74:75], v[66:67], 1, v[72:73]
	v_add_co_u32_e32 v74, vcc, 0x2000, v74
	v_cvt_pk_bf16_f32 v48, v48, s0
	s_nop 0
	v_addc_co_u32_e32 v75, vcc, 0, v75, vcc
	global_store_short v[74:75], v48, off nt
.LBB0_280:
	s_andn2_saveexec_b64 s[10:11], s[10:11]
	s_cbranch_execz .LBB0_282
	global_store_short v[72:73], v65, off nt

.LBB0_283:
	s_or_saveexec_b64 s[8:9], s[8:9]
	v_sub_u32_e32 v64, 0x1000, v66
	s_xor_b64 exec, exec, s[8:9]
	s_cbranch_execz .LBB0_285
	v_cvt_pk_bf16_f32 v48, v48, s0
	v_lshl_add_u64 v[74:75], v[64:65], 1, v[72:73]
	global_store_short v[74:75], v48, off nt
.LBB0_285:
	s_or_b64 exec, exec, s[8:9]
	v_bitop3_b32 v48, v68, s28, 1 bitop3:0xc8
	v_cvt_f32_u32_e32 v75, v48
	v_or_b32_e32 v74, v48, v69
	v_fmamk_f32 v96, v75, 0xbc44ade8, v90
	v_mul_f32_e64 v48, v91, |v96|
	v_mul_f32_e32 v48, 0x3fb8aa3b, v48
	v_exp_f32_e32 v48, v48
	v_ashrrev_i32_e32 v75, 31, v74
	v_lshlrev_b64 v[74:75], 14, v[74:75]
	v_lshl_add_u64 v[74:75], s[6:7], 0, v[74:75]
	v_add_f32_e32 v49, v49, v201
	v_mul_f32_e32 v48, v48, v49
	s_and_saveexec_b64 s[8:9], s[0:1]
	s_xor_b64 s[8:9], exec, s[8:9]
	s_cbranch_execz .LBB0_291
	s_and_saveexec_b64 s[10:11], s[4:5]
	s_xor_b64 s[10:11], exec, s[10:11]
	s_cbranch_execz .LBB0_288
	v_cvt_pk_bf16_f32 v76, v48, s0
	v_lshl_add_u64 v[48:49], v[66:67], 1, v[74:75]
	v_add_co_u32_e32 v48, vcc, 0x2000, v48
	s_nop 1
	v_addc_co_u32_e32 v49, vcc, 0, v49, vcc
	global_store_short v[48:49], v76, off nt
.LBB0_288:
	s_andn2_saveexec_b64 s[10:11], s[10:11]
	s_cbranch_execz .LBB0_290
	global_store_short v[74:75], v65, off nt

.LBB0_291:
	s_andn2_saveexec_b64 s[8:9], s[8:9]
	s_cbranch_execz .LBB0_293
	v_cvt_pk_bf16_f32 v76, v48, s0
	v_lshl_add_u64 v[48:49], v[64:65], 1, v[74:75]
	global_store_short v[48:49], v76, off nt
.LBB0_293:
	s_or_b64 exec, exec, s[8:9]
	v_bitop3_b32 v48, v68, s29, 2 bitop3:0xc8
	v_cvt_f32_u32_e32 v49, v48
	v_or_b32_e32 v48, v48, v69
	v_fmamk_f32 v98, v49, 0xbc44ade8, v90
	v_mul_f32_e64 v49, v91, |v98|
	v_mul_f32_e32 v49, 0x3fb8aa3b, v49
	v_exp_f32_e32 v78, v49
	v_ashrrev_i32_e32 v49, 31, v48
	v_lshlrev_b64 v[76:77], 14, v[48:49]
	v_lshl_add_u64 v[76:77], s[6:7], 0, v[76:77]
	v_add_f32_e32 v48, v50, v202
	v_mul_f32_e32 v48, v78, v48
	s_and_saveexec_b64 s[8:9], s[0:1]
	s_xor_b64 s[8:9], exec, s[8:9]
	s_cbranch_execz .LBB0_299
	s_and_saveexec_b64 s[10:11], s[4:5]
	s_xor_b64 s[10:11], exec, s[10:11]
	s_cbranch_execz .LBB0_296
	v_cvt_pk_bf16_f32 v50, v48, s0
	v_lshl_add_u64 v[48:49], v[66:67], 1, v[76:77]
	v_add_co_u32_e32 v48, vcc, 0x2000, v48
	s_nop 1
	v_addc_co_u32_e32 v49, vcc, 0, v49, vcc
	global_store_short v[48:49], v50, off nt
.LBB0_296:
	s_andn2_saveexec_b64 s[10:11], s[10:11]
	s_cbranch_execz .LBB0_298
	global_store_short v[76:77], v65, off nt

.LBB0_299:
	s_andn2_saveexec_b64 s[8:9], s[8:9]
	s_cbranch_execz .LBB0_301
	v_cvt_pk_bf16_f32 v50, v48, s0
	v_lshl_add_u64 v[48:49], v[64:65], 1, v[76:77]
	global_store_short v[48:49], v50, off nt
.LBB0_301:
	s_or_b64 exec, exec, s[8:9]
	v_bitop3_b32 v48, v68, s30, 3 bitop3:0xc8
	v_cvt_f32_u32_e32 v49, v48
	v_or_b32_e32 v48, v48, v69
	v_fmamk_f32 v100, v49, 0xbc44ade8, v90
	v_mul_f32_e64 v49, v91, |v100|
	v_mul_f32_e32 v49, 0x3fb8aa3b, v49
	v_exp_f32_e32 v50, v49
	v_ashrrev_i32_e32 v49, 31, v48
	v_lshlrev_b64 v[78:79], 14, v[48:49]
	v_add_f32_e32 v48, v51, v203
	v_mul_f32_e32 v48, v50, v48
	v_lshl_add_u64 v[50:51], s[6:7], 0, v[78:79]
	s_and_saveexec_b64 s[8:9], s[0:1]
	s_xor_b64 s[8:9], exec, s[8:9]
	s_cbranch_execz .LBB0_307
	s_and_saveexec_b64 s[10:11], s[4:5]
	s_xor_b64 s[10:11], exec, s[10:11]
	s_cbranch_execz .LBB0_304
	v_cvt_pk_bf16_f32 v78, v48, s0
	v_lshl_add_u64 v[48:49], v[66:67], 1, v[50:51]
	v_add_co_u32_e32 v48, vcc, 0x2000, v48
	s_nop 1
	v_addc_co_u32_e32 v49, vcc, 0, v49, vcc
	global_store_short v[48:49], v78, off nt
.LBB0_304:
	s_andn2_saveexec_b64 s[10:11], s[10:11]
	s_cbranch_execz .LBB0_306
	global_store_short v[50:51], v65, off nt

.LBB0_307:
	s_andn2_saveexec_b64 s[8:9], s[8:9]
	s_cbranch_execz .LBB0_309
	v_cvt_pk_bf16_f32 v78, v48, s0
	v_lshl_add_u64 v[48:49], v[64:65], 1, v[50:51]
	global_store_short v[48:49], v78, off nt
.LBB0_309:
	s_or_b64 exec, exec, s[8:9]
	v_bitop3_b32 v48, v68, s31, 8 bitop3:0xc8
	v_cvt_f32_u32_e32 v49, v48
	v_or_b32_e32 v48, v48, v69
	v_fmamk_f32 v102, v49, 0xbc44ade8, v90
	v_mul_f32_e64 v49, v91, |v102|
	v_mul_f32_e32 v49, 0x3fb8aa3b, v49
	v_exp_f32_e32 v80, v49
	v_ashrrev_i32_e32 v49, 31, v48
	v_lshlrev_b64 v[78:79], 14, v[48:49]
	v_lshl_add_u64 v[78:79], s[6:7], 0, v[78:79]
	v_add_f32_e32 v48, v52, v204
	v_mul_f32_e32 v48, v80, v48
	s_and_saveexec_b64 s[8:9], s[0:1]
	s_xor_b64 s[8:9], exec, s[8:9]
	s_cbranch_execz .LBB0_315
	s_and_saveexec_b64 s[10:11], s[4:5]
	s_xor_b64 s[10:11], exec, s[10:11]
	s_cbranch_execz .LBB0_312
	v_cvt_pk_bf16_f32 v52, v48, s0
	v_lshl_add_u64 v[48:49], v[66:67], 1, v[78:79]
	v_add_co_u32_e32 v48, vcc, 0x2000, v48
	s_nop 1
	v_addc_co_u32_e32 v49, vcc, 0, v49, vcc
	global_store_short v[48:49], v52, off nt
.LBB0_312:
	s_andn2_saveexec_b64 s[10:11], s[10:11]
	s_cbranch_execz .LBB0_314
	global_store_short v[78:79], v65, off nt

.LBB0_315:
	s_andn2_saveexec_b64 s[8:9], s[8:9]
	s_cbranch_execz .LBB0_317
	v_cvt_pk_bf16_f32 v52, v48, s0
	v_lshl_add_u64 v[48:49], v[64:65], 1, v[78:79]
	global_store_short v[48:49], v52, off nt
.LBB0_317:
	s_or_b64 exec, exec, s[8:9]
	v_bitop3_b32 v48, v68, s33, 9 bitop3:0xc8
	v_cvt_f32_u32_e32 v49, v48
	v_or_b32_e32 v48, v48, v69
	v_fmamk_f32 v104, v49, 0xbc44ade8, v90
	v_mul_f32_e64 v49, v91, |v104|
	v_mul_f32_e32 v49, 0x3fb8aa3b, v49
	v_exp_f32_e32 v52, v49
	v_ashrrev_i32_e32 v49, 31, v48
	v_lshlrev_b64 v[80:81], 14, v[48:49]
	v_add_f32_e32 v48, v53, v205
	v_mul_f32_e32 v48, v52, v48
	v_lshl_add_u64 v[52:53], s[6:7], 0, v[80:81]
	s_and_saveexec_b64 s[8:9], s[0:1]
	s_xor_b64 s[8:9], exec, s[8:9]
	s_cbranch_execz .LBB0_323
	s_and_saveexec_b64 s[10:11], s[4:5]
	s_xor_b64 s[10:11], exec, s[10:11]
	s_cbranch_execz .LBB0_320
	v_cvt_pk_bf16_f32 v80, v48, s0
	v_lshl_add_u64 v[48:49], v[66:67], 1, v[52:53]
	v_add_co_u32_e32 v48, vcc, 0x2000, v48
	s_nop 1
	v_addc_co_u32_e32 v49, vcc, 0, v49, vcc
	global_store_short v[48:49], v80, off nt
.LBB0_320:
	s_andn2_saveexec_b64 s[10:11], s[10:11]
	s_cbranch_execz .LBB0_322
	global_store_short v[52:53], v65, off nt

.LBB0_323:
	s_andn2_saveexec_b64 s[8:9], s[8:9]
	s_cbranch_execz .LBB0_325
	v_cvt_pk_bf16_f32 v80, v48, s0
	v_lshl_add_u64 v[48:49], v[64:65], 1, v[52:53]
	global_store_short v[48:49], v80, off nt
.LBB0_325:
	s_or_b64 exec, exec, s[8:9]
	v_bitop3_b32 v48, v68, s40, 10 bitop3:0xc8
	v_cvt_f32_u32_e32 v49, v48
	v_or_b32_e32 v48, v48, v69
	v_fmamk_f32 v106, v49, 0xbc44ade8, v90
	v_mul_f32_e64 v49, v91, |v106|
	v_mul_f32_e32 v49, 0x3fb8aa3b, v49
	v_exp_f32_e32 v82, v49
	v_ashrrev_i32_e32 v49, 31, v48
	v_lshlrev_b64 v[80:81], 14, v[48:49]
	v_lshl_add_u64 v[80:81], s[6:7], 0, v[80:81]
	v_add_f32_e32 v48, v54, v206
	v_mul_f32_e32 v48, v82, v48
	s_and_saveexec_b64 s[8:9], s[0:1]
	s_xor_b64 s[8:9], exec, s[8:9]
	s_cbranch_execz .LBB0_331
	s_and_saveexec_b64 s[10:11], s[4:5]
	s_xor_b64 s[10:11], exec, s[10:11]
	s_cbranch_execz .LBB0_328
	v_cvt_pk_bf16_f32 v54, v48, s0
	v_lshl_add_u64 v[48:49], v[66:67], 1, v[80:81]
	v_add_co_u32_e32 v48, vcc, 0x2000, v48
	s_nop 1
	v_addc_co_u32_e32 v49, vcc, 0, v49, vcc
	global_store_short v[48:49], v54, off nt
.LBB0_328:
	s_andn2_saveexec_b64 s[10:11], s[10:11]
	s_cbranch_execz .LBB0_330
	global_store_short v[80:81], v65, off nt

.LBB0_331:
	s_andn2_saveexec_b64 s[8:9], s[8:9]
	s_cbranch_execz .LBB0_333
	v_cvt_pk_bf16_f32 v54, v48, s0
	v_lshl_add_u64 v[48:49], v[64:65], 1, v[80:81]
	global_store_short v[48:49], v54, off nt
.LBB0_333:
	s_or_b64 exec, exec, s[8:9]
	v_bitop3_b32 v48, v68, s41, 11 bitop3:0xc8
	v_cvt_f32_u32_e32 v49, v48
	v_or_b32_e32 v48, v48, v69
	v_fmamk_f32 v108, v49, 0xbc44ade8, v90
	v_mul_f32_e64 v49, v91, |v108|
	v_mul_f32_e32 v49, 0x3fb8aa3b, v49
	v_exp_f32_e32 v54, v49
	v_ashrrev_i32_e32 v49, 31, v48
	v_lshlrev_b64 v[82:83], 14, v[48:49]
	v_add_f32_e32 v48, v55, v207
	v_mul_f32_e32 v48, v54, v48
	v_lshl_add_u64 v[54:55], s[6:7], 0, v[82:83]
	s_and_saveexec_b64 s[8:9], s[0:1]
	s_xor_b64 s[8:9], exec, s[8:9]
	s_cbranch_execz .LBB0_339
	s_and_saveexec_b64 s[10:11], s[4:5]
	s_xor_b64 s[10:11], exec, s[10:11]
	s_cbranch_execz .LBB0_336
	v_cvt_pk_bf16_f32 v82, v48, s0
	v_lshl_add_u64 v[48:49], v[66:67], 1, v[54:55]
	v_add_co_u32_e32 v48, vcc, 0x2000, v48
	s_nop 1
	v_addc_co_u32_e32 v49, vcc, 0, v49, vcc
	global_store_short v[48:49], v82, off nt
.LBB0_336:
	s_andn2_saveexec_b64 s[10:11], s[10:11]
	s_cbranch_execz .LBB0_338
	global_store_short v[54:55], v65, off nt

.LBB0_339:
	s_andn2_saveexec_b64 s[8:9], s[8:9]
	s_cbranch_execz .LBB0_341
	v_cvt_pk_bf16_f32 v82, v48, s0
	v_lshl_add_u64 v[48:49], v[64:65], 1, v[54:55]
	global_store_short v[48:49], v82, off nt
.LBB0_341:
	s_or_b64 exec, exec, s[8:9]
	v_bitop3_b32 v48, v68, s42, 16 bitop3:0xc8
	v_cvt_f32_u32_e32 v49, v48
	v_or_b32_e32 v48, v48, v69
	v_fmamk_f32 v110, v49, 0xbc44ade8, v90
	v_mul_f32_e64 v49, v91, |v110|
	v_mul_f32_e32 v49, 0x3fb8aa3b, v49
	v_exp_f32_e32 v84, v49
	v_ashrrev_i32_e32 v49, 31, v48
	v_lshlrev_b64 v[82:83], 14, v[48:49]
	v_lshl_add_u64 v[82:83], s[6:7], 0, v[82:83]
	v_add_f32_e32 v48, v56, v208
	v_mul_f32_e32 v48, v84, v48
	s_and_saveexec_b64 s[8:9], s[0:1]
	s_xor_b64 s[8:9], exec, s[8:9]
	s_cbranch_execz .LBB0_347
	s_and_saveexec_b64 s[10:11], s[4:5]
	s_xor_b64 s[10:11], exec, s[10:11]
	s_cbranch_execz .LBB0_344
	v_cvt_pk_bf16_f32 v56, v48, s0
	v_lshl_add_u64 v[48:49], v[66:67], 1, v[82:83]
	v_add_co_u32_e32 v48, vcc, 0x2000, v48
	s_nop 1
	v_addc_co_u32_e32 v49, vcc, 0, v49, vcc
	global_store_short v[48:49], v56, off nt
.LBB0_344:
	s_andn2_saveexec_b64 s[10:11], s[10:11]
	s_cbranch_execz .LBB0_346
	global_store_short v[82:83], v65, off nt

.LBB0_347:
	s_andn2_saveexec_b64 s[8:9], s[8:9]
	s_cbranch_execz .LBB0_349
	v_cvt_pk_bf16_f32 v56, v48, s0
	v_lshl_add_u64 v[48:49], v[64:65], 1, v[82:83]
	global_store_short v[48:49], v56, off nt
.LBB0_349:
	s_or_b64 exec, exec, s[8:9]
	v_bitop3_b32 v48, v68, s43, 17 bitop3:0xc8
	v_cvt_f32_u32_e32 v49, v48
	v_or_b32_e32 v48, v48, v69
	v_fmamk_f32 v112, v49, 0xbc44ade8, v90
	v_mul_f32_e64 v49, v91, |v112|
	v_mul_f32_e32 v49, 0x3fb8aa3b, v49
	v_exp_f32_e32 v56, v49
	v_ashrrev_i32_e32 v49, 31, v48
	v_lshlrev_b64 v[84:85], 14, v[48:49]
	v_add_f32_e32 v48, v57, v209
	v_mul_f32_e32 v48, v56, v48
	v_lshl_add_u64 v[56:57], s[6:7], 0, v[84:85]
	s_and_saveexec_b64 s[8:9], s[0:1]
	s_xor_b64 s[8:9], exec, s[8:9]
	s_cbranch_execz .LBB0_355
	s_and_saveexec_b64 s[10:11], s[4:5]
	s_xor_b64 s[10:11], exec, s[10:11]
	s_cbranch_execz .LBB0_352
	v_cvt_pk_bf16_f32 v84, v48, s0
	v_lshl_add_u64 v[48:49], v[66:67], 1, v[56:57]
	v_add_co_u32_e32 v48, vcc, 0x2000, v48
	s_nop 1
	v_addc_co_u32_e32 v49, vcc, 0, v49, vcc
	global_store_short v[48:49], v84, off nt
.LBB0_352:
	s_andn2_saveexec_b64 s[10:11], s[10:11]
	s_cbranch_execz .LBB0_354
	global_store_short v[56:57], v65, off nt

.LBB0_355:
	s_andn2_saveexec_b64 s[8:9], s[8:9]
	s_cbranch_execz .LBB0_357
	v_cvt_pk_bf16_f32 v84, v48, s0
	v_lshl_add_u64 v[48:49], v[64:65], 1, v[56:57]
	global_store_short v[48:49], v84, off nt
.LBB0_357:
	s_or_b64 exec, exec, s[8:9]
	v_bitop3_b32 v48, v68, s44, 18 bitop3:0xc8
	v_cvt_f32_u32_e32 v49, v48
	v_or_b32_e32 v48, v48, v69
	v_fmamk_f32 v114, v49, 0xbc44ade8, v90
	v_mul_f32_e64 v49, v91, |v114|
	v_mul_f32_e32 v49, 0x3fb8aa3b, v49
	v_exp_f32_e32 v86, v49
	v_ashrrev_i32_e32 v49, 31, v48
	v_lshlrev_b64 v[84:85], 14, v[48:49]
	v_lshl_add_u64 v[84:85], s[6:7], 0, v[84:85]
	v_add_f32_e32 v48, v58, v210
	v_mul_f32_e32 v48, v86, v48
	s_and_saveexec_b64 s[8:9], s[0:1]
	s_xor_b64 s[8:9], exec, s[8:9]
	s_cbranch_execz .LBB0_363
	s_and_saveexec_b64 s[10:11], s[4:5]
	s_xor_b64 s[10:11], exec, s[10:11]
	s_cbranch_execz .LBB0_360
	v_cvt_pk_bf16_f32 v58, v48, s0
	v_lshl_add_u64 v[48:49], v[66:67], 1, v[84:85]
	v_add_co_u32_e32 v48, vcc, 0x2000, v48
	s_nop 1
	v_addc_co_u32_e32 v49, vcc, 0, v49, vcc
	global_store_short v[48:49], v58, off nt
.LBB0_360:
	s_andn2_saveexec_b64 s[10:11], s[10:11]
	s_cbranch_execz .LBB0_362
	global_store_short v[84:85], v65, off nt

.LBB0_363:
	s_andn2_saveexec_b64 s[8:9], s[8:9]
	s_cbranch_execz .LBB0_365
	v_cvt_pk_bf16_f32 v58, v48, s0
	v_lshl_add_u64 v[48:49], v[64:65], 1, v[84:85]
	global_store_short v[48:49], v58, off nt
.LBB0_365:
	s_or_b64 exec, exec, s[8:9]
	v_bitop3_b32 v48, v68, s45, 19 bitop3:0xc8
	v_cvt_f32_u32_e32 v49, v48
	v_or_b32_e32 v48, v48, v69
	v_fmamk_f32 v116, v49, 0xbc44ade8, v90
	v_mul_f32_e64 v49, v91, |v116|
	v_mul_f32_e32 v49, 0x3fb8aa3b, v49
	v_exp_f32_e32 v58, v49
	v_ashrrev_i32_e32 v49, 31, v48
	v_lshlrev_b64 v[86:87], 14, v[48:49]
	v_add_f32_e32 v48, v59, v211
	v_mul_f32_e32 v48, v58, v48
	v_lshl_add_u64 v[58:59], s[6:7], 0, v[86:87]
	s_and_saveexec_b64 s[8:9], s[0:1]
	s_xor_b64 s[8:9], exec, s[8:9]
	s_cbranch_execz .LBB0_371
	s_and_saveexec_b64 s[10:11], s[4:5]
	s_xor_b64 s[10:11], exec, s[10:11]
	s_cbranch_execz .LBB0_368
	v_cvt_pk_bf16_f32 v86, v48, s0
	v_lshl_add_u64 v[48:49], v[66:67], 1, v[58:59]
	v_add_co_u32_e32 v48, vcc, 0x2000, v48
	s_nop 1
	v_addc_co_u32_e32 v49, vcc, 0, v49, vcc
	global_store_short v[48:49], v86, off nt
.LBB0_368:
	s_andn2_saveexec_b64 s[10:11], s[10:11]
	s_cbranch_execz .LBB0_370
	global_store_short v[58:59], v65, off nt

.LBB0_371:
	s_andn2_saveexec_b64 s[8:9], s[8:9]
	s_cbranch_execz .LBB0_373
	v_cvt_pk_bf16_f32 v86, v48, s0
	v_lshl_add_u64 v[48:49], v[64:65], 1, v[58:59]
	global_store_short v[48:49], v86, off nt
.LBB0_373:
	s_or_b64 exec, exec, s[8:9]
	v_bitop3_b32 v48, v68, s46, 24 bitop3:0xc8
	v_cvt_f32_u32_e32 v49, v48
	v_or_b32_e32 v48, v48, v69
	v_fmamk_f32 v118, v49, 0xbc44ade8, v90
	v_mul_f32_e64 v49, v91, |v118|
	v_mul_f32_e32 v49, 0x3fb8aa3b, v49
	v_exp_f32_e32 v88, v49
	v_ashrrev_i32_e32 v49, 31, v48
	v_lshlrev_b64 v[86:87], 14, v[48:49]
	v_lshl_add_u64 v[86:87], s[6:7], 0, v[86:87]
	v_add_f32_e32 v48, v60, v212
	v_mul_f32_e32 v48, v88, v48
	s_and_saveexec_b64 s[8:9], s[0:1]
	s_xor_b64 s[8:9], exec, s[8:9]
	s_cbranch_execz .LBB0_379
	s_and_saveexec_b64 s[10:11], s[4:5]
	s_xor_b64 s[10:11], exec, s[10:11]
	s_cbranch_execz .LBB0_376
	v_cvt_pk_bf16_f32 v60, v48, s0
	v_lshl_add_u64 v[48:49], v[66:67], 1, v[86:87]
	v_add_co_u32_e32 v48, vcc, 0x2000, v48
	s_nop 1
	v_addc_co_u32_e32 v49, vcc, 0, v49, vcc
	global_store_short v[48:49], v60, off nt
.LBB0_376:
	s_andn2_saveexec_b64 s[10:11], s[10:11]
	s_cbranch_execz .LBB0_378
	global_store_short v[86:87], v65, off nt

.LBB0_379:
	s_andn2_saveexec_b64 s[8:9], s[8:9]
	s_cbranch_execz .LBB0_381
	v_cvt_pk_bf16_f32 v60, v48, s0
	v_lshl_add_u64 v[48:49], v[64:65], 1, v[86:87]
	global_store_short v[48:49], v60, off nt
.LBB0_381:
	s_or_b64 exec, exec, s[8:9]
	v_bitop3_b32 v48, v68, s47, 25 bitop3:0xc8
	v_cvt_f32_u32_e32 v49, v48
	v_or_b32_e32 v48, v48, v69
	v_fmamk_f32 v120, v49, 0xbc44ade8, v90
	v_mul_f32_e64 v49, v91, |v120|
	v_mul_f32_e32 v49, 0x3fb8aa3b, v49
	v_exp_f32_e32 v60, v49
	v_ashrrev_i32_e32 v49, 31, v48
	v_lshlrev_b64 v[88:89], 14, v[48:49]
	v_add_f32_e32 v48, v61, v213
	v_mul_f32_e32 v48, v60, v48
	v_lshl_add_u64 v[60:61], s[6:7], 0, v[88:89]
	s_and_saveexec_b64 s[8:9], s[0:1]
	s_xor_b64 s[8:9], exec, s[8:9]
	s_cbranch_execz .LBB0_387
	s_and_saveexec_b64 s[10:11], s[4:5]
	s_xor_b64 s[10:11], exec, s[10:11]
	s_cbranch_execz .LBB0_384
	v_cvt_pk_bf16_f32 v88, v48, s0
	v_lshl_add_u64 v[48:49], v[66:67], 1, v[60:61]
	v_add_co_u32_e32 v48, vcc, 0x2000, v48
	s_nop 1
	v_addc_co_u32_e32 v49, vcc, 0, v49, vcc
	global_store_short v[48:49], v88, off nt
.LBB0_384:
	s_andn2_saveexec_b64 s[10:11], s[10:11]
	s_cbranch_execz .LBB0_386
	global_store_short v[60:61], v65, off nt

.LBB0_387:
	s_andn2_saveexec_b64 s[8:9], s[8:9]
	s_cbranch_execz .LBB0_389
	v_cvt_pk_bf16_f32 v88, v48, s0
	v_lshl_add_u64 v[48:49], v[64:65], 1, v[60:61]
	global_store_short v[48:49], v88, off nt
.LBB0_389:
	s_or_b64 exec, exec, s[8:9]
	v_bitop3_b32 v48, v68, s48, 26 bitop3:0xc8
	v_cvt_f32_u32_e32 v49, v48
	v_or_b32_e32 v48, v48, v69
	v_fmamk_f32 v122, v49, 0xbc44ade8, v90
	v_mul_f32_e64 v49, v91, |v122|
	v_mul_f32_e32 v49, 0x3fb8aa3b, v49
	v_exp_f32_e32 v92, v49
	v_ashrrev_i32_e32 v49, 31, v48
	v_lshlrev_b64 v[88:89], 14, v[48:49]
	v_lshl_add_u64 v[88:89], s[6:7], 0, v[88:89]
	v_add_f32_e32 v48, v62, v214
	v_mul_f32_e32 v48, v92, v48
	s_and_saveexec_b64 s[8:9], s[0:1]
	s_xor_b64 s[8:9], exec, s[8:9]
	s_cbranch_execz .LBB0_395
	s_and_saveexec_b64 s[10:11], s[4:5]
	s_xor_b64 s[10:11], exec, s[10:11]
	s_cbranch_execz .LBB0_392
	v_cvt_pk_bf16_f32 v62, v48, s0
	v_lshl_add_u64 v[48:49], v[66:67], 1, v[88:89]
	v_add_co_u32_e32 v48, vcc, 0x2000, v48
	s_nop 1
	v_addc_co_u32_e32 v49, vcc, 0, v49, vcc
	global_store_short v[48:49], v62, off nt
.LBB0_392:
	s_andn2_saveexec_b64 s[10:11], s[10:11]
	s_cbranch_execz .LBB0_394
	global_store_short v[88:89], v65, off nt

.LBB0_395:
	s_andn2_saveexec_b64 s[8:9], s[8:9]
	s_cbranch_execz .LBB0_397
	v_cvt_pk_bf16_f32 v62, v48, s0
	v_lshl_add_u64 v[48:49], v[64:65], 1, v[88:89]
	global_store_short v[48:49], v62, off nt
.LBB0_397:
	s_or_b64 exec, exec, s[8:9]
	v_bitop3_b32 v48, v68, s49, 27 bitop3:0xc8
	v_cvt_f32_u32_e32 v49, v48
	v_or_b32_e32 v48, v48, v69
	v_fmamk_f32 v124, v49, 0xbc44ade8, v90
	v_mul_f32_e64 v49, v91, |v124|
	v_mul_f32_e32 v49, 0x3fb8aa3b, v49
	v_exp_f32_e32 v62, v49
	v_ashrrev_i32_e32 v49, 31, v48
	v_lshlrev_b64 v[126:127], 14, v[48:49]
	v_add_f32_e32 v48, v63, v215
	v_mul_f32_e32 v48, v62, v48
	v_lshl_add_u64 v[62:63], s[6:7], 0, v[126:127]
	s_and_saveexec_b64 s[8:9], s[0:1]
	s_xor_b64 s[8:9], exec, s[8:9]
	s_cbranch_execz .LBB0_403
	s_and_saveexec_b64 s[10:11], s[4:5]
	s_xor_b64 s[10:11], exec, s[10:11]
	s_cbranch_execz .LBB0_400
	v_cvt_pk_bf16_f32 v92, v48, s0
	v_lshl_add_u64 v[48:49], v[66:67], 1, v[62:63]
	v_add_co_u32_e32 v48, vcc, 0x2000, v48
	s_nop 1
	v_addc_co_u32_e32 v49, vcc, 0, v49, vcc
	global_store_short v[48:49], v92, off nt
.LBB0_400:
	s_andn2_saveexec_b64 s[10:11], s[10:11]
	s_cbranch_execz .LBB0_402
	global_store_short v[62:63], v65, off nt

.LBB0_403:
	s_andn2_saveexec_b64 s[8:9], s[8:9]
	s_cbranch_execz .LBB0_405
	v_cvt_pk_bf16_f32 v92, v48, s0
	v_lshl_add_u64 v[48:49], v[64:65], 1, v[62:63]
	global_store_short v[48:49], v92, off nt
.LBB0_405:
	s_or_b64 exec, exec, s[8:9]
	v_or_b32_e32 v48, 32, v66
	v_cvt_f32_i32_e32 v48, v48
	v_add_f32_e32 v32, v32, v200
	v_mul_f32_e32 v92, 0xb9800801, v48
	v_mul_f32_e64 v48, v92, |v94|
	v_mul_f32_e32 v48, 0x3fb8aa3b, v48
	v_exp_f32_e32 v48, v48
	s_nop 0
	v_mul_f32_e32 v32, v48, v32
	v_cvt_pk_bf16_f32 v32, v32, s0
	s_and_saveexec_b64 s[8:9], s[0:1]
	s_xor_b64 s[8:9], exec, s[8:9]
	s_cbranch_execz .LBB0_407
	v_lshl_add_u64 v[48:49], v[66:67], 1, v[72:73]
	v_add_co_u32_e32 v48, vcc, 0x2000, v48
	s_nop 1
	v_addc_co_u32_e32 v49, vcc, 0, v49, vcc
	global_store_short v[48:49], v32, off offset:64 nt
.LBB0_407:
	s_or_saveexec_b64 s[8:9], s[8:9]
	v_sub_u32_e32 v48, 0xfe0, v66
	v_mov_b32_e32 v49, v65
	s_xor_b64 exec, exec, s[8:9]
	s_cbranch_execz .LBB0_409
	v_lshl_add_u64 v[72:73], v[48:49], 1, v[72:73]
	global_store_short v[72:73], v32, off nt
.LBB0_409:
	s_or_b64 exec, exec, s[8:9]
	v_mul_f32_e64 v32, v92, |v96|
	v_mul_f32_e32 v32, 0x3fb8aa3b, v32
	v_exp_f32_e32 v32, v32
	v_add_f32_e32 v33, v33, v201
	v_mul_f32_e32 v32, v32, v33
	v_cvt_pk_bf16_f32 v32, v32, s0
	s_and_saveexec_b64 s[8:9], s[0:1]
	s_xor_b64 s[8:9], exec, s[8:9]
	s_cbranch_execz .LBB0_411
	v_lshl_add_u64 v[72:73], v[66:67], 1, v[74:75]
	v_add_co_u32_e32 v72, vcc, 0x2000, v72
	s_nop 1
	v_addc_co_u32_e32 v73, vcc, 0, v73, vcc
	global_store_short v[72:73], v32, off offset:64 nt
.LBB0_411:
	s_andn2_saveexec_b64 s[8:9], s[8:9]
	s_cbranch_execz .LBB0_413
	v_lshl_add_u64 v[72:73], v[48:49], 1, v[74:75]
	global_store_short v[72:73], v32, off nt
.LBB0_413:
	s_or_b64 exec, exec, s[8:9]
	v_mul_f32_e64 v32, v92, |v98|
	v_mul_f32_e32 v32, 0x3fb8aa3b, v32
	v_exp_f32_e32 v32, v32
	v_add_f32_e32 v33, v34, v202
	v_mul_f32_e32 v32, v32, v33
	v_cvt_pk_bf16_f32 v32, v32, s0
	s_and_saveexec_b64 s[8:9], s[0:1]
	s_xor_b64 s[8:9], exec, s[8:9]
	s_cbranch_execz .LBB0_415
	v_lshl_add_u64 v[72:73], v[66:67], 1, v[76:77]
	v_add_co_u32_e32 v72, vcc, 0x2000, v72
	s_nop 1
	v_addc_co_u32_e32 v73, vcc, 0, v73, vcc
	global_store_short v[72:73], v32, off offset:64 nt
.LBB0_415:
	s_andn2_saveexec_b64 s[8:9], s[8:9]
	s_cbranch_execz .LBB0_417
	v_lshl_add_u64 v[72:73], v[48:49], 1, v[76:77]
	global_store_short v[72:73], v32, off nt
.LBB0_417:
	s_or_b64 exec, exec, s[8:9]
	v_mul_f32_e64 v32, v92, |v100|
	v_mul_f32_e32 v32, 0x3fb8aa3b, v32
	v_exp_f32_e32 v32, v32
	v_add_f32_e32 v33, v35, v203
	v_mul_f32_e32 v32, v32, v33
	v_cvt_pk_bf16_f32 v32, v32, s0
	s_and_saveexec_b64 s[8:9], s[0:1]
	s_xor_b64 s[8:9], exec, s[8:9]
	s_cbranch_execz .LBB0_419
	v_lshl_add_u64 v[34:35], v[66:67], 1, v[50:51]
	v_add_co_u32_e32 v34, vcc, 0x2000, v34
	s_nop 1
	v_addc_co_u32_e32 v35, vcc, 0, v35, vcc
	global_store_short v[34:35], v32, off offset:64 nt
.LBB0_419:
	s_andn2_saveexec_b64 s[8:9], s[8:9]
	s_cbranch_execz .LBB0_421
	v_lshl_add_u64 v[34:35], v[48:49], 1, v[50:51]
	global_store_short v[34:35], v32, off nt
.LBB0_421:
	s_or_b64 exec, exec, s[8:9]
	v_mul_f32_e64 v32, v92, |v102|
	v_mul_f32_e32 v32, 0x3fb8aa3b, v32
	v_exp_f32_e32 v32, v32
	v_add_f32_e32 v33, v36, v204
	v_mul_f32_e32 v32, v32, v33
	v_cvt_pk_bf16_f32 v32, v32, s0
	s_and_saveexec_b64 s[8:9], s[0:1]
	s_xor_b64 s[8:9], exec, s[8:9]
	s_cbranch_execz .LBB0_423
	v_lshl_add_u64 v[34:35], v[66:67], 1, v[78:79]
	v_add_co_u32_e32 v34, vcc, 0x2000, v34
	s_nop 1
	v_addc_co_u32_e32 v35, vcc, 0, v35, vcc
	global_store_short v[34:35], v32, off offset:64 nt
.LBB0_423:
	s_andn2_saveexec_b64 s[8:9], s[8:9]
	s_cbranch_execz .LBB0_425
	v_lshl_add_u64 v[34:35], v[48:49], 1, v[78:79]
	global_store_short v[34:35], v32, off nt
.LBB0_425:
	s_or_b64 exec, exec, s[8:9]
	v_mul_f32_e64 v32, v92, |v104|
	v_mul_f32_e32 v32, 0x3fb8aa3b, v32
	v_exp_f32_e32 v32, v32
	v_add_f32_e32 v33, v37, v205
	v_mul_f32_e32 v32, v32, v33
	v_cvt_pk_bf16_f32 v32, v32, s0
	s_and_saveexec_b64 s[8:9], s[0:1]
	s_xor_b64 s[8:9], exec, s[8:9]
	s_cbranch_execz .LBB0_427
	v_lshl_add_u64 v[34:35], v[66:67], 1, v[52:53]
	v_add_co_u32_e32 v34, vcc, 0x2000, v34
	s_nop 1
	v_addc_co_u32_e32 v35, vcc, 0, v35, vcc
	global_store_short v[34:35], v32, off offset:64 nt
.LBB0_427:
	s_andn2_saveexec_b64 s[8:9], s[8:9]
	s_cbranch_execz .LBB0_429
	v_lshl_add_u64 v[34:35], v[48:49], 1, v[52:53]
	global_store_short v[34:35], v32, off nt
.LBB0_429:
	s_or_b64 exec, exec, s[8:9]
	v_mul_f32_e64 v32, v92, |v106|
	v_mul_f32_e32 v32, 0x3fb8aa3b, v32
	v_exp_f32_e32 v32, v32
	v_add_f32_e32 v33, v38, v206
	v_mul_f32_e32 v32, v32, v33
	v_cvt_pk_bf16_f32 v32, v32, s0
	s_and_saveexec_b64 s[8:9], s[0:1]
	s_xor_b64 s[8:9], exec, s[8:9]
	s_cbranch_execz .LBB0_431
	v_lshl_add_u64 v[34:35], v[66:67], 1, v[80:81]
	v_add_co_u32_e32 v34, vcc, 0x2000, v34
	s_nop 1
	v_addc_co_u32_e32 v35, vcc, 0, v35, vcc
	global_store_short v[34:35], v32, off offset:64 nt
.LBB0_431:
	s_andn2_saveexec_b64 s[8:9], s[8:9]
	s_cbranch_execz .LBB0_433
	v_lshl_add_u64 v[34:35], v[48:49], 1, v[80:81]
	global_store_short v[34:35], v32, off nt
.LBB0_433:
	s_or_b64 exec, exec, s[8:9]
	v_mul_f32_e64 v32, v92, |v108|
	v_mul_f32_e32 v32, 0x3fb8aa3b, v32
	v_exp_f32_e32 v32, v32
	v_add_f32_e32 v33, v39, v207
	v_mul_f32_e32 v32, v32, v33
	v_cvt_pk_bf16_f32 v32, v32, s0
	s_and_saveexec_b64 s[8:9], s[0:1]
	s_xor_b64 s[8:9], exec, s[8:9]
	s_cbranch_execz .LBB0_435
	v_lshl_add_u64 v[34:35], v[66:67], 1, v[54:55]
	v_add_co_u32_e32 v34, vcc, 0x2000, v34
	s_nop 1
	v_addc_co_u32_e32 v35, vcc, 0, v35, vcc
	global_store_short v[34:35], v32, off offset:64 nt
.LBB0_435:
	s_andn2_saveexec_b64 s[8:9], s[8:9]
	s_cbranch_execz .LBB0_437
	v_lshl_add_u64 v[34:35], v[48:49], 1, v[54:55]
	global_store_short v[34:35], v32, off nt
.LBB0_437:
	s_or_b64 exec, exec, s[8:9]
	v_mul_f32_e64 v32, v92, |v110|
	v_mul_f32_e32 v32, 0x3fb8aa3b, v32
	v_exp_f32_e32 v32, v32
	v_add_f32_e32 v33, v40, v208
	v_mul_f32_e32 v32, v32, v33
	v_cvt_pk_bf16_f32 v32, v32, s0
	s_and_saveexec_b64 s[8:9], s[0:1]
	s_xor_b64 s[8:9], exec, s[8:9]
	s_cbranch_execz .LBB0_439
	v_lshl_add_u64 v[34:35], v[66:67], 1, v[82:83]
	v_add_co_u32_e32 v34, vcc, 0x2000, v34
	s_nop 1
	v_addc_co_u32_e32 v35, vcc, 0, v35, vcc
	global_store_short v[34:35], v32, off offset:64 nt
.LBB0_439:
	s_andn2_saveexec_b64 s[8:9], s[8:9]
	s_cbranch_execz .LBB0_441
	v_lshl_add_u64 v[34:35], v[48:49], 1, v[82:83]
	global_store_short v[34:35], v32, off nt
.LBB0_441:
	s_or_b64 exec, exec, s[8:9]
	v_mul_f32_e64 v32, v92, |v112|
	v_mul_f32_e32 v32, 0x3fb8aa3b, v32
	v_exp_f32_e32 v32, v32
	v_add_f32_e32 v33, v41, v209
	v_mul_f32_e32 v32, v32, v33
	v_cvt_pk_bf16_f32 v32, v32, s0
	s_and_saveexec_b64 s[8:9], s[0:1]
	s_xor_b64 s[8:9], exec, s[8:9]
	s_cbranch_execz .LBB0_443
	v_lshl_add_u64 v[34:35], v[66:67], 1, v[56:57]
	v_add_co_u32_e32 v34, vcc, 0x2000, v34
	s_nop 1
	v_addc_co_u32_e32 v35, vcc, 0, v35, vcc
	global_store_short v[34:35], v32, off offset:64 nt
.LBB0_443:
	s_andn2_saveexec_b64 s[8:9], s[8:9]
	s_cbranch_execz .LBB0_445
	v_lshl_add_u64 v[34:35], v[48:49], 1, v[56:57]
	global_store_short v[34:35], v32, off nt
.LBB0_445:
	s_or_b64 exec, exec, s[8:9]
	v_mul_f32_e64 v32, v92, |v114|
	v_mul_f32_e32 v32, 0x3fb8aa3b, v32
	v_exp_f32_e32 v32, v32
	v_add_f32_e32 v33, v42, v210
	v_mul_f32_e32 v32, v32, v33
	v_cvt_pk_bf16_f32 v32, v32, s0
	s_and_saveexec_b64 s[8:9], s[0:1]
	s_xor_b64 s[8:9], exec, s[8:9]
	s_cbranch_execz .LBB0_447
	v_lshl_add_u64 v[34:35], v[66:67], 1, v[84:85]
	v_add_co_u32_e32 v34, vcc, 0x2000, v34
	s_nop 1
	v_addc_co_u32_e32 v35, vcc, 0, v35, vcc
	global_store_short v[34:35], v32, off offset:64 nt
.LBB0_447:
	s_andn2_saveexec_b64 s[8:9], s[8:9]
	s_cbranch_execz .LBB0_449
	v_lshl_add_u64 v[34:35], v[48:49], 1, v[84:85]
	global_store_short v[34:35], v32, off nt
.LBB0_449:
	s_or_b64 exec, exec, s[8:9]
	v_mul_f32_e64 v32, v92, |v116|
	v_mul_f32_e32 v32, 0x3fb8aa3b, v32
	v_exp_f32_e32 v32, v32
	v_add_f32_e32 v33, v43, v211
	v_mul_f32_e32 v32, v32, v33
	v_cvt_pk_bf16_f32 v32, v32, s0
	s_and_saveexec_b64 s[8:9], s[0:1]
	s_xor_b64 s[8:9], exec, s[8:9]
	s_cbranch_execz .LBB0_451
	v_lshl_add_u64 v[34:35], v[66:67], 1, v[58:59]
	v_add_co_u32_e32 v34, vcc, 0x2000, v34
	s_nop 1
	v_addc_co_u32_e32 v35, vcc, 0, v35, vcc
	global_store_short v[34:35], v32, off offset:64 nt
.LBB0_451:
	s_andn2_saveexec_b64 s[8:9], s[8:9]
	s_cbranch_execz .LBB0_453
	v_lshl_add_u64 v[34:35], v[48:49], 1, v[58:59]
	global_store_short v[34:35], v32, off nt
.LBB0_453:
	s_or_b64 exec, exec, s[8:9]
	v_mul_f32_e64 v32, v92, |v118|
	v_mul_f32_e32 v32, 0x3fb8aa3b, v32
	v_exp_f32_e32 v32, v32
	v_add_f32_e32 v33, v44, v212
	v_mul_f32_e32 v32, v32, v33
	v_cvt_pk_bf16_f32 v32, v32, s0
	s_and_saveexec_b64 s[8:9], s[0:1]
	s_xor_b64 s[8:9], exec, s[8:9]
	s_cbranch_execz .LBB0_455
	v_lshl_add_u64 v[34:35], v[66:67], 1, v[86:87]
	v_add_co_u32_e32 v34, vcc, 0x2000, v34
	s_nop 1
	v_addc_co_u32_e32 v35, vcc, 0, v35, vcc
	global_store_short v[34:35], v32, off offset:64 nt
.LBB0_455:
	s_andn2_saveexec_b64 s[8:9], s[8:9]
	s_cbranch_execz .LBB0_457
	v_lshl_add_u64 v[34:35], v[48:49], 1, v[86:87]
	global_store_short v[34:35], v32, off nt
.LBB0_457:
	s_or_b64 exec, exec, s[8:9]
	v_mul_f32_e64 v32, v92, |v120|
	v_mul_f32_e32 v32, 0x3fb8aa3b, v32
	v_exp_f32_e32 v32, v32
	v_add_f32_e32 v33, v45, v213
	v_mul_f32_e32 v32, v32, v33
	v_cvt_pk_bf16_f32 v32, v32, s0
	s_and_saveexec_b64 s[8:9], s[0:1]
	s_xor_b64 s[8:9], exec, s[8:9]
	s_cbranch_execz .LBB0_459
	v_lshl_add_u64 v[34:35], v[66:67], 1, v[60:61]
	v_add_co_u32_e32 v34, vcc, 0x2000, v34
	s_nop 1
	v_addc_co_u32_e32 v35, vcc, 0, v35, vcc
	global_store_short v[34:35], v32, off offset:64 nt
.LBB0_459:
	s_andn2_saveexec_b64 s[8:9], s[8:9]
	s_cbranch_execz .LBB0_461
	v_lshl_add_u64 v[34:35], v[48:49], 1, v[60:61]
	global_store_short v[34:35], v32, off nt
.LBB0_461:
	s_or_b64 exec, exec, s[8:9]
	v_mul_f32_e64 v32, v92, |v122|
	v_mul_f32_e32 v32, 0x3fb8aa3b, v32
	v_exp_f32_e32 v32, v32
	v_add_f32_e32 v33, v46, v214
	v_mul_f32_e32 v32, v32, v33
	v_cvt_pk_bf16_f32 v32, v32, s0
	s_and_saveexec_b64 s[8:9], s[0:1]
	s_xor_b64 s[8:9], exec, s[8:9]
	s_cbranch_execz .LBB0_463
	v_lshl_add_u64 v[34:35], v[66:67], 1, v[88:89]
	v_add_co_u32_e32 v34, vcc, 0x2000, v34
	s_nop 1
	v_addc_co_u32_e32 v35, vcc, 0, v35, vcc
	global_store_short v[34:35], v32, off offset:64 nt
.LBB0_463:
	s_andn2_saveexec_b64 s[8:9], s[8:9]
	s_cbranch_execz .LBB0_465
	v_lshl_add_u64 v[34:35], v[48:49], 1, v[88:89]
	global_store_short v[34:35], v32, off nt
.LBB0_465:
	s_or_b64 exec, exec, s[8:9]
	v_mul_f32_e64 v32, v92, |v124|
	v_mul_f32_e32 v32, 0x3fb8aa3b, v32
	v_exp_f32_e32 v32, v32
	v_add_f32_e32 v33, v47, v215
	v_mul_f32_e32 v32, v32, v33
	v_cvt_pk_bf16_f32 v32, v32, s0
	s_and_saveexec_b64 s[8:9], s[0:1]
	s_xor_b64 s[8:9], exec, s[8:9]
	s_cbranch_execz .LBB0_467
	v_lshl_add_u64 v[34:35], v[66:67], 1, v[62:63]
	v_add_co_u32_e32 v34, vcc, 0x2000, v34
	s_nop 1
	v_addc_co_u32_e32 v35, vcc, 0, v35, vcc
	global_store_short v[34:35], v32, off offset:64 nt
.LBB0_467:
	s_andn2_saveexec_b64 s[8:9], s[8:9]
	s_cbranch_execz .LBB0_469
	v_lshl_add_u64 v[34:35], v[48:49], 1, v[62:63]
	global_store_short v[34:35], v32, off nt
.LBB0_469:
	s_or_b64 exec, exec, s[8:9]
	v_bitop3_b32 v32, v68, s54, 32 bitop3:0xc8
	v_cvt_f32_u32_e32 v33, v32
	v_or_b32_e32 v32, v32, v69
	v_fmamk_f32 v51, v33, 0xbc44ade8, v90
	v_mul_f32_e64 v33, v91, |v51|
	v_mul_f32_e32 v33, 0x3fb8aa3b, v33
	v_exp_f32_e32 v34, v33
	v_ashrrev_i32_e32 v33, 31, v32
	v_lshlrev_b64 v[32:33], 14, v[32:33]
	v_lshl_add_u64 v[32:33], s[6:7], 0, v[32:33]
	v_add_f32_e32 v16, v16, v216
	v_mul_f32_e32 v16, v34, v16
	s_and_saveexec_b64 s[8:9], s[0:1]
	s_xor_b64 s[8:9], exec, s[8:9]
	s_cbranch_execz .LBB0_475
	s_and_saveexec_b64 s[10:11], s[4:5]
	s_xor_b64 s[10:11], exec, s[10:11]
	s_cbranch_execz .LBB0_472
	v_lshl_add_u64 v[34:35], v[66:67], 1, v[32:33]
	v_add_co_u32_e32 v34, vcc, 0x2000, v34
	v_cvt_pk_bf16_f32 v16, v16, s0
	s_nop 0
	v_addc_co_u32_e32 v35, vcc, 0, v35, vcc
	global_store_short v[34:35], v16, off nt
.LBB0_472:
	s_andn2_saveexec_b64 s[10:11], s[10:11]
	s_cbranch_execz .LBB0_474
	global_store_short v[32:33], v65, off nt

.LBB0_475:
	s_andn2_saveexec_b64 s[8:9], s[8:9]
	s_cbranch_execz .LBB0_477
	v_cvt_pk_bf16_f32 v16, v16, s0
	v_lshl_add_u64 v[34:35], v[64:65], 1, v[32:33]
	global_store_short v[34:35], v16, off nt
.LBB0_477:
	s_or_b64 exec, exec, s[8:9]
	v_bitop3_b32 v16, v68, s55, 33 bitop3:0xc8
	v_cvt_f32_u32_e32 v35, v16
	v_or_b32_e32 v34, v16, v69
	v_fmamk_f32 v53, v35, 0xbc44ade8, v90
	v_mul_f32_e64 v16, v91, |v53|
	v_mul_f32_e32 v16, 0x3fb8aa3b, v16
	v_exp_f32_e32 v16, v16
	v_ashrrev_i32_e32 v35, 31, v34
	v_lshlrev_b64 v[36:37], 14, v[34:35]
	v_add_f32_e32 v17, v17, v217
	v_mul_f32_e32 v34, v16, v17
	v_lshl_add_u64 v[16:17], s[6:7], 0, v[36:37]
	s_and_saveexec_b64 s[8:9], s[0:1]
	s_xor_b64 s[8:9], exec, s[8:9]
	s_cbranch_execz .LBB0_483
	s_and_saveexec_b64 s[10:11], s[4:5]
	s_xor_b64 s[10:11], exec, s[10:11]
	s_cbranch_execz .LBB0_480
	v_cvt_pk_bf16_f32 v36, v34, s0
	v_lshl_add_u64 v[34:35], v[66:67], 1, v[16:17]
	v_add_co_u32_e32 v34, vcc, 0x2000, v34
	s_nop 1
	v_addc_co_u32_e32 v35, vcc, 0, v35, vcc
	global_store_short v[34:35], v36, off nt
.LBB0_480:
	s_andn2_saveexec_b64 s[10:11], s[10:11]
	s_cbranch_execz .LBB0_482
	global_store_short v[16:17], v65, off nt

.LBB0_483:
	s_andn2_saveexec_b64 s[8:9], s[8:9]
	s_cbranch_execz .LBB0_485
	v_cvt_pk_bf16_f32 v36, v34, s0
	v_lshl_add_u64 v[34:35], v[64:65], 1, v[16:17]
	global_store_short v[34:35], v36, off nt
.LBB0_485:
	s_or_b64 exec, exec, s[8:9]
	v_bitop3_b32 v34, v68, s58, 34 bitop3:0xc8
	v_cvt_f32_u32_e32 v35, v34
	v_or_b32_e32 v34, v34, v69
	v_fmamk_f32 v55, v35, 0xbc44ade8, v90
	v_mul_f32_e64 v35, v91, |v55|
	v_mul_f32_e32 v35, 0x3fb8aa3b, v35
	v_exp_f32_e32 v36, v35
	v_ashrrev_i32_e32 v35, 31, v34
	v_lshlrev_b64 v[34:35], 14, v[34:35]
	v_lshl_add_u64 v[34:35], s[6:7], 0, v[34:35]
	v_add_f32_e32 v18, v18, v218
	v_mul_f32_e32 v18, v36, v18
	s_and_saveexec_b64 s[8:9], s[0:1]
	s_xor_b64 s[8:9], exec, s[8:9]
	s_cbranch_execz .LBB0_491
	s_and_saveexec_b64 s[10:11], s[4:5]
	s_xor_b64 s[10:11], exec, s[10:11]
	s_cbranch_execz .LBB0_488
	v_lshl_add_u64 v[36:37], v[66:67], 1, v[34:35]
	v_add_co_u32_e32 v36, vcc, 0x2000, v36
	v_cvt_pk_bf16_f32 v18, v18, s0
	s_nop 0
	v_addc_co_u32_e32 v37, vcc, 0, v37, vcc
	global_store_short v[36:37], v18, off nt
.LBB0_488:
	s_andn2_saveexec_b64 s[10:11], s[10:11]
	s_cbranch_execz .LBB0_490
	global_store_short v[34:35], v65, off nt

.LBB0_491:
	s_andn2_saveexec_b64 s[8:9], s[8:9]
	s_cbranch_execz .LBB0_493
	v_cvt_pk_bf16_f32 v18, v18, s0
	v_lshl_add_u64 v[36:37], v[64:65], 1, v[34:35]
	global_store_short v[36:37], v18, off nt
.LBB0_493:
	s_or_b64 exec, exec, s[8:9]
	v_bitop3_b32 v18, v68, s59, 35 bitop3:0xc8
	v_cvt_f32_u32_e32 v37, v18
	v_or_b32_e32 v36, v18, v69
	v_fmamk_f32 v57, v37, 0xbc44ade8, v90
	v_mul_f32_e64 v18, v91, |v57|
	v_mul_f32_e32 v18, 0x3fb8aa3b, v18
	v_exp_f32_e32 v18, v18
	v_ashrrev_i32_e32 v37, 31, v36
	v_lshlrev_b64 v[38:39], 14, v[36:37]
	v_add_f32_e32 v19, v19, v219
	v_mul_f32_e32 v36, v18, v19
	v_lshl_add_u64 v[18:19], s[6:7], 0, v[38:39]
	s_and_saveexec_b64 s[8:9], s[0:1]
	s_xor_b64 s[8:9], exec, s[8:9]
	s_cbranch_execz .LBB0_499
	s_and_saveexec_b64 s[10:11], s[4:5]
	s_xor_b64 s[10:11], exec, s[10:11]
	s_cbranch_execz .LBB0_496
	v_cvt_pk_bf16_f32 v38, v36, s0
	v_lshl_add_u64 v[36:37], v[66:67], 1, v[18:19]
	v_add_co_u32_e32 v36, vcc, 0x2000, v36
	s_nop 1
	v_addc_co_u32_e32 v37, vcc, 0, v37, vcc
	global_store_short v[36:37], v38, off nt
.LBB0_496:
	s_andn2_saveexec_b64 s[10:11], s[10:11]
	s_cbranch_execz .LBB0_498
	global_store_short v[18:19], v65, off nt

.LBB0_499:
	s_andn2_saveexec_b64 s[8:9], s[8:9]
	s_cbranch_execz .LBB0_501
	v_cvt_pk_bf16_f32 v38, v36, s0
	v_lshl_add_u64 v[36:37], v[64:65], 1, v[18:19]
	global_store_short v[36:37], v38, off nt
.LBB0_501:
	s_or_b64 exec, exec, s[8:9]
	v_bitop3_b32 v36, v68, s60, 40 bitop3:0xc8
	v_cvt_f32_u32_e32 v37, v36
	v_or_b32_e32 v36, v36, v69
	v_fmamk_f32 v59, v37, 0xbc44ade8, v90
	v_mul_f32_e64 v37, v91, |v59|
	v_mul_f32_e32 v37, 0x3fb8aa3b, v37
	v_exp_f32_e32 v38, v37
	v_ashrrev_i32_e32 v37, 31, v36
	v_lshlrev_b64 v[36:37], 14, v[36:37]
	v_lshl_add_u64 v[36:37], s[6:7], 0, v[36:37]
	v_add_f32_e32 v20, v20, v220
	v_mul_f32_e32 v20, v38, v20
	s_and_saveexec_b64 s[8:9], s[0:1]
	s_xor_b64 s[8:9], exec, s[8:9]
	s_cbranch_execz .LBB0_507
	s_and_saveexec_b64 s[10:11], s[4:5]
	s_xor_b64 s[10:11], exec, s[10:11]
	s_cbranch_execz .LBB0_504
	v_lshl_add_u64 v[38:39], v[66:67], 1, v[36:37]
	v_add_co_u32_e32 v38, vcc, 0x2000, v38
	v_cvt_pk_bf16_f32 v20, v20, s0
	s_nop 0
	v_addc_co_u32_e32 v39, vcc, 0, v39, vcc
	global_store_short v[38:39], v20, off nt
.LBB0_504:
	s_andn2_saveexec_b64 s[10:11], s[10:11]
	s_cbranch_execz .LBB0_506
	global_store_short v[36:37], v65, off nt

.LBB0_507:
	s_andn2_saveexec_b64 s[8:9], s[8:9]
	s_cbranch_execz .LBB0_509
	v_cvt_pk_bf16_f32 v20, v20, s0
	v_lshl_add_u64 v[38:39], v[64:65], 1, v[36:37]
	global_store_short v[38:39], v20, off nt
.LBB0_509:
	s_or_b64 exec, exec, s[8:9]
	v_bitop3_b32 v20, v68, s61, 41 bitop3:0xc8
	v_cvt_f32_u32_e32 v39, v20
	v_or_b32_e32 v38, v20, v69
	v_fmamk_f32 v61, v39, 0xbc44ade8, v90
	v_mul_f32_e64 v20, v91, |v61|
	v_mul_f32_e32 v20, 0x3fb8aa3b, v20
	v_exp_f32_e32 v20, v20
	v_ashrrev_i32_e32 v39, 31, v38
	v_lshlrev_b64 v[40:41], 14, v[38:39]
	v_add_f32_e32 v21, v21, v221
	v_mul_f32_e32 v38, v20, v21
	v_lshl_add_u64 v[20:21], s[6:7], 0, v[40:41]
	s_and_saveexec_b64 s[8:9], s[0:1]
	s_xor_b64 s[8:9], exec, s[8:9]
	s_cbranch_execz .LBB0_515
	s_and_saveexec_b64 s[10:11], s[4:5]
	s_xor_b64 s[10:11], exec, s[10:11]
	s_cbranch_execz .LBB0_512
	v_cvt_pk_bf16_f32 v40, v38, s0
	v_lshl_add_u64 v[38:39], v[66:67], 1, v[20:21]
	v_add_co_u32_e32 v38, vcc, 0x2000, v38
	s_nop 1
	v_addc_co_u32_e32 v39, vcc, 0, v39, vcc
	global_store_short v[38:39], v40, off nt
.LBB0_512:
	s_andn2_saveexec_b64 s[10:11], s[10:11]
	s_cbranch_execz .LBB0_514
	global_store_short v[20:21], v65, off nt

.LBB0_515:
	s_andn2_saveexec_b64 s[8:9], s[8:9]
	s_cbranch_execz .LBB0_517
	v_cvt_pk_bf16_f32 v40, v38, s0
	v_lshl_add_u64 v[38:39], v[64:65], 1, v[20:21]
	global_store_short v[38:39], v40, off nt
.LBB0_517:
	s_or_b64 exec, exec, s[8:9]
	v_bitop3_b32 v38, v68, s62, 42 bitop3:0xc8
	v_cvt_f32_u32_e32 v39, v38
	v_or_b32_e32 v38, v38, v69
	v_fmamk_f32 v63, v39, 0xbc44ade8, v90
	v_mul_f32_e64 v39, v91, |v63|
	v_mul_f32_e32 v39, 0x3fb8aa3b, v39
	v_exp_f32_e32 v40, v39
	v_ashrrev_i32_e32 v39, 31, v38
	v_lshlrev_b64 v[38:39], 14, v[38:39]
	v_lshl_add_u64 v[38:39], s[6:7], 0, v[38:39]
	v_add_f32_e32 v22, v22, v222
	v_mul_f32_e32 v22, v40, v22
	s_and_saveexec_b64 s[8:9], s[0:1]
	s_xor_b64 s[8:9], exec, s[8:9]
	s_cbranch_execz .LBB0_523
	s_and_saveexec_b64 s[10:11], s[4:5]
	s_xor_b64 s[10:11], exec, s[10:11]
	s_cbranch_execz .LBB0_520
	v_lshl_add_u64 v[40:41], v[66:67], 1, v[38:39]
	v_add_co_u32_e32 v40, vcc, 0x2000, v40
	v_cvt_pk_bf16_f32 v22, v22, s0
	s_nop 0
	v_addc_co_u32_e32 v41, vcc, 0, v41, vcc
	global_store_short v[40:41], v22, off nt
.LBB0_520:
	s_andn2_saveexec_b64 s[10:11], s[10:11]
	s_cbranch_execz .LBB0_522
	global_store_short v[38:39], v65, off nt

.LBB0_523:
	s_andn2_saveexec_b64 s[8:9], s[8:9]
	s_cbranch_execz .LBB0_525
	v_cvt_pk_bf16_f32 v22, v22, s0
	v_lshl_add_u64 v[40:41], v[64:65], 1, v[38:39]
	global_store_short v[40:41], v22, off nt
.LBB0_525:
	s_or_b64 exec, exec, s[8:9]
	v_bitop3_b32 v22, v68, s63, 43 bitop3:0xc8
	v_cvt_f32_u32_e32 v41, v22
	v_or_b32_e32 v40, v22, v69
	v_fmamk_f32 v73, v41, 0xbc44ade8, v90
	v_mul_f32_e64 v22, v91, |v73|
	v_mul_f32_e32 v22, 0x3fb8aa3b, v22
	v_exp_f32_e32 v22, v22
	v_ashrrev_i32_e32 v41, 31, v40
	v_lshlrev_b64 v[42:43], 14, v[40:41]
	v_add_f32_e32 v23, v23, v223
	v_mul_f32_e32 v40, v22, v23
	v_lshl_add_u64 v[22:23], s[6:7], 0, v[42:43]
	s_and_saveexec_b64 s[8:9], s[0:1]
	s_xor_b64 s[8:9], exec, s[8:9]
	s_cbranch_execz .LBB0_531
	s_and_saveexec_b64 s[10:11], s[4:5]
	s_xor_b64 s[10:11], exec, s[10:11]
	s_cbranch_execz .LBB0_528
	v_cvt_pk_bf16_f32 v42, v40, s0
	v_lshl_add_u64 v[40:41], v[66:67], 1, v[22:23]
	v_add_co_u32_e32 v40, vcc, 0x2000, v40
	s_nop 1
	v_addc_co_u32_e32 v41, vcc, 0, v41, vcc
	global_store_short v[40:41], v42, off nt
.LBB0_528:
	s_andn2_saveexec_b64 s[10:11], s[10:11]
	s_cbranch_execz .LBB0_530
	global_store_short v[22:23], v65, off nt

.LBB0_531:
	s_andn2_saveexec_b64 s[8:9], s[8:9]
	s_cbranch_execz .LBB0_533
	v_cvt_pk_bf16_f32 v42, v40, s0
	v_lshl_add_u64 v[40:41], v[64:65], 1, v[22:23]
	global_store_short v[40:41], v42, off nt
.LBB0_533:
	s_or_b64 exec, exec, s[8:9]
	v_bitop3_b32 v40, v68, s66, 48 bitop3:0xc8
	v_cvt_f32_u32_e32 v41, v40
	v_or_b32_e32 v40, v40, v69
	v_fmamk_f32 v75, v41, 0xbc44ade8, v90
	v_mul_f32_e64 v41, v91, |v75|
	v_mul_f32_e32 v41, 0x3fb8aa3b, v41
	v_exp_f32_e32 v42, v41
	v_ashrrev_i32_e32 v41, 31, v40
	v_lshlrev_b64 v[40:41], 14, v[40:41]
	v_lshl_add_u64 v[40:41], s[6:7], 0, v[40:41]
	v_add_f32_e32 v24, v24, v224
	v_mul_f32_e32 v24, v42, v24
	s_and_saveexec_b64 s[8:9], s[0:1]
	s_xor_b64 s[8:9], exec, s[8:9]
	s_cbranch_execz .LBB0_539
	s_and_saveexec_b64 s[10:11], s[4:5]
	s_xor_b64 s[10:11], exec, s[10:11]
	s_cbranch_execz .LBB0_536
	v_lshl_add_u64 v[42:43], v[66:67], 1, v[40:41]
	v_add_co_u32_e32 v42, vcc, 0x2000, v42
	v_cvt_pk_bf16_f32 v24, v24, s0
	s_nop 0
	v_addc_co_u32_e32 v43, vcc, 0, v43, vcc
	global_store_short v[42:43], v24, off nt
.LBB0_536:
	s_andn2_saveexec_b64 s[10:11], s[10:11]
	s_cbranch_execz .LBB0_538
	global_store_short v[40:41], v65, off nt

.LBB0_539:
	s_andn2_saveexec_b64 s[8:9], s[8:9]
	s_cbranch_execz .LBB0_541
	v_cvt_pk_bf16_f32 v24, v24, s0
	v_lshl_add_u64 v[42:43], v[64:65], 1, v[40:41]
	global_store_short v[42:43], v24, off nt
.LBB0_541:
	s_or_b64 exec, exec, s[8:9]
	v_bitop3_b32 v24, v68, s67, 49 bitop3:0xc8
	v_cvt_f32_u32_e32 v43, v24
	v_or_b32_e32 v42, v24, v69
	v_fmamk_f32 v77, v43, 0xbc44ade8, v90
	v_mul_f32_e64 v24, v91, |v77|
	v_mul_f32_e32 v24, 0x3fb8aa3b, v24
	v_exp_f32_e32 v24, v24
	v_ashrrev_i32_e32 v43, 31, v42
	v_lshlrev_b64 v[44:45], 14, v[42:43]
	v_add_f32_e32 v25, v25, v225
	v_mul_f32_e32 v42, v24, v25
	v_lshl_add_u64 v[24:25], s[6:7], 0, v[44:45]
	s_and_saveexec_b64 s[8:9], s[0:1]
	s_xor_b64 s[8:9], exec, s[8:9]
	s_cbranch_execz .LBB0_547
	s_and_saveexec_b64 s[10:11], s[4:5]
	s_xor_b64 s[10:11], exec, s[10:11]
	s_cbranch_execz .LBB0_544
	v_cvt_pk_bf16_f32 v44, v42, s0
	v_lshl_add_u64 v[42:43], v[66:67], 1, v[24:25]
	v_add_co_u32_e32 v42, vcc, 0x2000, v42
	s_nop 1
	v_addc_co_u32_e32 v43, vcc, 0, v43, vcc
	global_store_short v[42:43], v44, off nt
.LBB0_544:
	s_andn2_saveexec_b64 s[10:11], s[10:11]
	s_cbranch_execz .LBB0_546
	global_store_short v[24:25], v65, off nt

.LBB0_547:
	s_andn2_saveexec_b64 s[8:9], s[8:9]
	s_cbranch_execz .LBB0_549
	v_cvt_pk_bf16_f32 v44, v42, s0
	v_lshl_add_u64 v[42:43], v[64:65], 1, v[24:25]
	global_store_short v[42:43], v44, off nt
.LBB0_549:
	s_or_b64 exec, exec, s[8:9]
	v_bitop3_b32 v42, v68, s68, 50 bitop3:0xc8
	v_cvt_f32_u32_e32 v43, v42
	v_or_b32_e32 v42, v42, v69
	v_fmamk_f32 v79, v43, 0xbc44ade8, v90
	v_mul_f32_e64 v43, v91, |v79|
	v_mul_f32_e32 v43, 0x3fb8aa3b, v43
	v_exp_f32_e32 v44, v43
	v_ashrrev_i32_e32 v43, 31, v42
	v_lshlrev_b64 v[42:43], 14, v[42:43]
	v_lshl_add_u64 v[42:43], s[6:7], 0, v[42:43]
	v_add_f32_e32 v26, v26, v226
	v_mul_f32_e32 v26, v44, v26
	s_and_saveexec_b64 s[8:9], s[0:1]
	s_xor_b64 s[8:9], exec, s[8:9]
	s_cbranch_execz .LBB0_555
	s_and_saveexec_b64 s[10:11], s[4:5]
	s_xor_b64 s[10:11], exec, s[10:11]
	s_cbranch_execz .LBB0_552
	v_lshl_add_u64 v[44:45], v[66:67], 1, v[42:43]
	v_add_co_u32_e32 v44, vcc, 0x2000, v44
	v_cvt_pk_bf16_f32 v26, v26, s0
	s_nop 0
	v_addc_co_u32_e32 v45, vcc, 0, v45, vcc
	global_store_short v[44:45], v26, off nt
.LBB0_552:
	s_andn2_saveexec_b64 s[10:11], s[10:11]
	s_cbranch_execz .LBB0_554
	global_store_short v[42:43], v65, off nt

.LBB0_555:
	s_andn2_saveexec_b64 s[8:9], s[8:9]
	s_cbranch_execz .LBB0_557
	v_cvt_pk_bf16_f32 v26, v26, s0
	v_lshl_add_u64 v[44:45], v[64:65], 1, v[42:43]
	global_store_short v[44:45], v26, off nt
.LBB0_557:
	s_or_b64 exec, exec, s[8:9]
	v_bitop3_b32 v26, v68, s69, 51 bitop3:0xc8
	v_cvt_f32_u32_e32 v45, v26
	v_or_b32_e32 v44, v26, v69
	v_fmamk_f32 v81, v45, 0xbc44ade8, v90
	v_mul_f32_e64 v26, v91, |v81|
	v_mul_f32_e32 v26, 0x3fb8aa3b, v26
	v_exp_f32_e32 v26, v26
	v_ashrrev_i32_e32 v45, 31, v44
	v_lshlrev_b64 v[46:47], 14, v[44:45]
	v_add_f32_e32 v27, v27, v227
	v_mul_f32_e32 v44, v26, v27
	v_lshl_add_u64 v[26:27], s[6:7], 0, v[46:47]
	s_and_saveexec_b64 s[8:9], s[0:1]
	s_xor_b64 s[8:9], exec, s[8:9]
	s_cbranch_execz .LBB0_563
	s_and_saveexec_b64 s[10:11], s[4:5]
	s_xor_b64 s[10:11], exec, s[10:11]
	s_cbranch_execz .LBB0_560
	v_cvt_pk_bf16_f32 v46, v44, s0
	v_lshl_add_u64 v[44:45], v[66:67], 1, v[26:27]
	v_add_co_u32_e32 v44, vcc, 0x2000, v44
	s_nop 1
	v_addc_co_u32_e32 v45, vcc, 0, v45, vcc
	global_store_short v[44:45], v46, off nt
.LBB0_560:
	s_andn2_saveexec_b64 s[10:11], s[10:11]
	s_cbranch_execz .LBB0_562
	global_store_short v[26:27], v65, off nt

.LBB0_563:
	s_andn2_saveexec_b64 s[8:9], s[8:9]
	s_cbranch_execz .LBB0_565
	v_cvt_pk_bf16_f32 v46, v44, s0
	v_lshl_add_u64 v[44:45], v[64:65], 1, v[26:27]
	global_store_short v[44:45], v46, off nt
.LBB0_565:
	s_or_b64 exec, exec, s[8:9]
	v_bitop3_b32 v44, v68, s72, 56 bitop3:0xc8
	v_cvt_f32_u32_e32 v45, v44
	v_or_b32_e32 v44, v44, v69
	v_fmamk_f32 v83, v45, 0xbc44ade8, v90
	v_mul_f32_e64 v45, v91, |v83|
	v_mul_f32_e32 v45, 0x3fb8aa3b, v45
	v_exp_f32_e32 v46, v45
	v_ashrrev_i32_e32 v45, 31, v44
	v_lshlrev_b64 v[44:45], 14, v[44:45]
	v_lshl_add_u64 v[44:45], s[6:7], 0, v[44:45]
	v_add_f32_e32 v28, v28, v228
	v_mul_f32_e32 v28, v46, v28
	s_and_saveexec_b64 s[8:9], s[0:1]
	s_xor_b64 s[8:9], exec, s[8:9]
	s_cbranch_execz .LBB0_571
	s_and_saveexec_b64 s[10:11], s[4:5]
	s_xor_b64 s[10:11], exec, s[10:11]
	s_cbranch_execz .LBB0_568
	v_lshl_add_u64 v[46:47], v[66:67], 1, v[44:45]
	v_add_co_u32_e32 v46, vcc, 0x2000, v46
	v_cvt_pk_bf16_f32 v28, v28, s0
	s_nop 0
	v_addc_co_u32_e32 v47, vcc, 0, v47, vcc
	global_store_short v[46:47], v28, off nt
.LBB0_568:
	s_andn2_saveexec_b64 s[10:11], s[10:11]
	s_cbranch_execz .LBB0_570
	global_store_short v[44:45], v65, off nt

.LBB0_571:
	s_andn2_saveexec_b64 s[8:9], s[8:9]
	s_cbranch_execz .LBB0_573
	v_cvt_pk_bf16_f32 v28, v28, s0
	v_lshl_add_u64 v[46:47], v[64:65], 1, v[44:45]
	global_store_short v[46:47], v28, off nt
.LBB0_573:
	s_or_b64 exec, exec, s[8:9]
	v_bitop3_b32 v28, v68, s73, 57 bitop3:0xc8
	v_cvt_f32_u32_e32 v47, v28
	v_or_b32_e32 v46, v28, v69
	v_fmamk_f32 v85, v47, 0xbc44ade8, v90
	v_mul_f32_e64 v28, v91, |v85|
	v_mul_f32_e32 v28, 0x3fb8aa3b, v28
	v_exp_f32_e32 v28, v28
	v_ashrrev_i32_e32 v47, 31, v46
	v_lshlrev_b64 v[86:87], 14, v[46:47]
	v_add_f32_e32 v29, v29, v229
	v_mul_f32_e32 v46, v28, v29
	v_lshl_add_u64 v[28:29], s[6:7], 0, v[86:87]
	s_and_saveexec_b64 s[8:9], s[0:1]
	s_xor_b64 s[8:9], exec, s[8:9]
	s_cbranch_execz .LBB0_579
	s_and_saveexec_b64 s[10:11], s[4:5]
	s_xor_b64 s[10:11], exec, s[10:11]
	s_cbranch_execz .LBB0_576
	v_cvt_pk_bf16_f32 v86, v46, s0
	v_lshl_add_u64 v[46:47], v[66:67], 1, v[28:29]
	v_add_co_u32_e32 v46, vcc, 0x2000, v46
	s_nop 1
	v_addc_co_u32_e32 v47, vcc, 0, v47, vcc
	global_store_short v[46:47], v86, off nt
.LBB0_576:
	s_andn2_saveexec_b64 s[10:11], s[10:11]
	s_cbranch_execz .LBB0_578
	global_store_short v[28:29], v65, off nt

.LBB0_579:
	s_andn2_saveexec_b64 s[8:9], s[8:9]
	s_cbranch_execz .LBB0_581
	v_cvt_pk_bf16_f32 v86, v46, s0
	v_lshl_add_u64 v[46:47], v[64:65], 1, v[28:29]
	global_store_short v[46:47], v86, off nt
.LBB0_581:
	s_or_b64 exec, exec, s[8:9]
	v_bitop3_b32 v46, v68, s80, 58 bitop3:0xc8
	v_cvt_f32_u32_e32 v47, v46
	v_or_b32_e32 v46, v46, v69
	v_fmamk_f32 v87, v47, 0xbc44ade8, v90
	v_mul_f32_e64 v47, v91, |v87|
	v_mul_f32_e32 v47, 0x3fb8aa3b, v47
	v_exp_f32_e32 v88, v47
	v_ashrrev_i32_e32 v47, 31, v46
	v_lshlrev_b64 v[46:47], 14, v[46:47]
	v_lshl_add_u64 v[46:47], s[6:7], 0, v[46:47]
	v_add_f32_e32 v30, v30, v230
	v_mul_f32_e32 v30, v88, v30
	s_and_saveexec_b64 s[8:9], s[0:1]
	s_xor_b64 s[8:9], exec, s[8:9]
	s_cbranch_execz .LBB0_587
	s_and_saveexec_b64 s[10:11], s[4:5]
	s_xor_b64 s[10:11], exec, s[10:11]
	s_cbranch_execz .LBB0_584
	v_lshl_add_u64 v[88:89], v[66:67], 1, v[46:47]
	v_add_co_u32_e32 v88, vcc, 0x2000, v88
	v_cvt_pk_bf16_f32 v30, v30, s0
	s_nop 0
	v_addc_co_u32_e32 v89, vcc, 0, v89, vcc
	global_store_short v[88:89], v30, off nt
.LBB0_584:
	s_andn2_saveexec_b64 s[10:11], s[10:11]
	s_cbranch_execz .LBB0_586
	global_store_short v[46:47], v65, off nt

.LBB0_587:
	s_andn2_saveexec_b64 s[8:9], s[8:9]
	s_cbranch_execz .LBB0_589
	v_cvt_pk_bf16_f32 v30, v30, s0
	v_lshl_add_u64 v[88:89], v[64:65], 1, v[46:47]
	global_store_short v[88:89], v30, off nt
.LBB0_589:
	s_or_b64 exec, exec, s[8:9]
	v_bitop3_b32 v30, v68, s81, 59 bitop3:0xc8
	v_cvt_f32_u32_e32 v68, v30
	v_or_b32_e32 v88, v30, v69
	v_ashrrev_i32_e32 v89, 31, v88
	v_lshlrev_b64 v[88:89], 14, v[88:89]
	v_fmamk_f32 v68, v68, 0xbc44ade8, v90
	v_mul_f32_e64 v30, v91, |v68|
	v_mul_f32_e32 v30, 0x3fb8aa3b, v30
	v_exp_f32_e32 v30, v30
	v_add_f32_e32 v31, v31, v231
	v_mul_f32_e32 v69, v30, v31
	v_lshl_add_u64 v[30:31], s[6:7], 0, v[88:89]
	s_and_saveexec_b64 s[8:9], s[0:1]
	s_xor_b64 s[8:9], exec, s[8:9]
	s_cbranch_execz .LBB0_595
	s_and_saveexec_b64 s[10:11], s[4:5]
	s_xor_b64 s[4:5], exec, s[10:11]
	s_cbranch_execz .LBB0_592
	v_lshl_add_u64 v[88:89], v[66:67], 1, v[30:31]
	v_add_co_u32_e32 v88, vcc, 0x2000, v88
	v_cvt_pk_bf16_f32 v64, v69, s0
	s_nop 0
	v_addc_co_u32_e32 v89, vcc, 0, v89, vcc
	global_store_short v[88:89], v64, off nt
.LBB0_592:
	s_andn2_saveexec_b64 s[4:5], s[4:5]
	s_cbranch_execz .LBB0_594
	global_store_short v[30:31], v65, off nt

.LBB0_595:
	s_andn2_saveexec_b64 s[4:5], s[8:9]
	s_cbranch_execz .LBB0_597
	v_cvt_pk_bf16_f32 v69, v69, s0
	v_lshl_add_u64 v[88:89], v[64:65], 1, v[30:31]
	global_store_short v[88:89], v69, off nt
.LBB0_597:
	s_or_b64 exec, exec, s[4:5]
	v_mul_f32_e64 v51, v92, |v51|
	v_mul_f32_e32 v51, 0x3fb8aa3b, v51
	v_exp_f32_e32 v51, v51
	v_add_f32_e32 v0, v0, v216
	v_mul_f32_e32 v0, v51, v0
	v_cvt_pk_bf16_f32 v0, v0, s0
	s_and_saveexec_b64 s[4:5], s[0:1]
	s_xor_b64 s[4:5], exec, s[4:5]
	s_cbranch_execz .LBB0_599
	v_lshl_add_u64 v[32:33], v[66:67], 1, v[32:33]
	v_add_co_u32_e32 v32, vcc, 0x2000, v32
	s_nop 1
	v_addc_co_u32_e32 v33, vcc, 0, v33, vcc
	global_store_short v[32:33], v0, off offset:64 nt
.LBB0_599:
	s_andn2_saveexec_b64 s[4:5], s[4:5]
	s_cbranch_execz .LBB0_601
	v_lshl_add_u64 v[32:33], v[48:49], 1, v[32:33]
	global_store_short v[32:33], v0, off nt
.LBB0_601:
	s_or_b64 exec, exec, s[4:5]
	v_mul_f32_e64 v0, v92, |v53|
	v_mul_f32_e32 v0, 0x3fb8aa3b, v0
	v_exp_f32_e32 v0, v0
	v_add_f32_e32 v1, v1, v217
	v_mul_f32_e32 v0, v0, v1
	v_cvt_pk_bf16_f32 v0, v0, s0
	s_and_saveexec_b64 s[4:5], s[0:1]
	s_xor_b64 s[4:5], exec, s[4:5]
	s_cbranch_execz .LBB0_603
	v_lshl_add_u64 v[16:17], v[66:67], 1, v[16:17]
	v_add_co_u32_e32 v16, vcc, 0x2000, v16
	s_nop 1
	v_addc_co_u32_e32 v17, vcc, 0, v17, vcc
	global_store_short v[16:17], v0, off offset:64 nt
.LBB0_603:
	s_andn2_saveexec_b64 s[4:5], s[4:5]
	s_cbranch_execz .LBB0_605
	v_lshl_add_u64 v[16:17], v[48:49], 1, v[16:17]
	global_store_short v[16:17], v0, off nt
.LBB0_605:
	s_or_b64 exec, exec, s[4:5]
	v_mul_f32_e64 v0, v92, |v55|
	v_mul_f32_e32 v0, 0x3fb8aa3b, v0
	v_exp_f32_e32 v0, v0
	v_add_f32_e32 v1, v2, v218
	v_mul_f32_e32 v0, v0, v1
	v_cvt_pk_bf16_f32 v0, v0, s0
	s_and_saveexec_b64 s[4:5], s[0:1]
	s_xor_b64 s[4:5], exec, s[4:5]
	s_cbranch_execz .LBB0_607
	v_lshl_add_u64 v[16:17], v[66:67], 1, v[34:35]
	v_add_co_u32_e32 v16, vcc, 0x2000, v16
	s_nop 1
	v_addc_co_u32_e32 v17, vcc, 0, v17, vcc
	global_store_short v[16:17], v0, off offset:64 nt
.LBB0_607:
	s_andn2_saveexec_b64 s[4:5], s[4:5]
	s_cbranch_execz .LBB0_609
	v_lshl_add_u64 v[16:17], v[48:49], 1, v[34:35]
	global_store_short v[16:17], v0, off nt
.LBB0_609:
	s_or_b64 exec, exec, s[4:5]
	v_mul_f32_e64 v0, v92, |v57|
	v_mul_f32_e32 v0, 0x3fb8aa3b, v0
	v_exp_f32_e32 v0, v0
	v_add_f32_e32 v1, v3, v219
	v_mul_f32_e32 v0, v0, v1
	v_cvt_pk_bf16_f32 v0, v0, s0
	s_and_saveexec_b64 s[4:5], s[0:1]
	s_xor_b64 s[4:5], exec, s[4:5]
	s_cbranch_execz .LBB0_611
	v_lshl_add_u64 v[2:3], v[66:67], 1, v[18:19]
	v_add_co_u32_e32 v2, vcc, 0x2000, v2
	s_nop 1
	v_addc_co_u32_e32 v3, vcc, 0, v3, vcc
	global_store_short v[2:3], v0, off offset:64 nt
.LBB0_611:
	s_andn2_saveexec_b64 s[4:5], s[4:5]
	s_cbranch_execz .LBB0_613
	v_lshl_add_u64 v[2:3], v[48:49], 1, v[18:19]
	global_store_short v[2:3], v0, off nt
.LBB0_613:
	s_or_b64 exec, exec, s[4:5]
	v_mul_f32_e64 v0, v92, |v59|
	v_mul_f32_e32 v0, 0x3fb8aa3b, v0
	v_exp_f32_e32 v0, v0
	v_add_f32_e32 v1, v4, v220
	v_mul_f32_e32 v0, v0, v1
	v_cvt_pk_bf16_f32 v0, v0, s0
	s_and_saveexec_b64 s[4:5], s[0:1]
	s_xor_b64 s[4:5], exec, s[4:5]
	s_cbranch_execz .LBB0_615
	v_lshl_add_u64 v[2:3], v[66:67], 1, v[36:37]
	v_add_co_u32_e32 v2, vcc, 0x2000, v2
	s_nop 1
	v_addc_co_u32_e32 v3, vcc, 0, v3, vcc
	global_store_short v[2:3], v0, off offset:64 nt
.LBB0_615:
	s_andn2_saveexec_b64 s[4:5], s[4:5]
	s_cbranch_execz .LBB0_617
	v_lshl_add_u64 v[2:3], v[48:49], 1, v[36:37]
	global_store_short v[2:3], v0, off nt
.LBB0_617:
	s_or_b64 exec, exec, s[4:5]
	v_mul_f32_e64 v0, v92, |v61|
	v_mul_f32_e32 v0, 0x3fb8aa3b, v0
	v_exp_f32_e32 v0, v0
	v_add_f32_e32 v1, v5, v221
	v_mul_f32_e32 v0, v0, v1
	v_cvt_pk_bf16_f32 v0, v0, s0
	s_and_saveexec_b64 s[4:5], s[0:1]
	s_xor_b64 s[4:5], exec, s[4:5]
	s_cbranch_execz .LBB0_619
	v_lshl_add_u64 v[2:3], v[66:67], 1, v[20:21]
	v_add_co_u32_e32 v2, vcc, 0x2000, v2
	s_nop 1
	v_addc_co_u32_e32 v3, vcc, 0, v3, vcc
	global_store_short v[2:3], v0, off offset:64 nt
.LBB0_619:
	s_andn2_saveexec_b64 s[4:5], s[4:5]
	s_cbranch_execz .LBB0_621
	v_lshl_add_u64 v[2:3], v[48:49], 1, v[20:21]
	global_store_short v[2:3], v0, off nt
.LBB0_621:
	s_or_b64 exec, exec, s[4:5]
	v_mul_f32_e64 v0, v92, |v63|
	v_mul_f32_e32 v0, 0x3fb8aa3b, v0
	v_exp_f32_e32 v0, v0
	v_add_f32_e32 v1, v6, v222
	v_mul_f32_e32 v0, v0, v1
	v_cvt_pk_bf16_f32 v0, v0, s0
	s_and_saveexec_b64 s[4:5], s[0:1]
	s_xor_b64 s[4:5], exec, s[4:5]
	s_cbranch_execz .LBB0_623
	v_lshl_add_u64 v[2:3], v[66:67], 1, v[38:39]
	v_add_co_u32_e32 v2, vcc, 0x2000, v2
	s_nop 1
	v_addc_co_u32_e32 v3, vcc, 0, v3, vcc
	global_store_short v[2:3], v0, off offset:64 nt
.LBB0_623:
	s_andn2_saveexec_b64 s[4:5], s[4:5]
	s_cbranch_execz .LBB0_625
	v_lshl_add_u64 v[2:3], v[48:49], 1, v[38:39]
	global_store_short v[2:3], v0, off nt
.LBB0_625:
	s_or_b64 exec, exec, s[4:5]
	v_mul_f32_e64 v0, v92, |v73|
	v_mul_f32_e32 v0, 0x3fb8aa3b, v0
	v_exp_f32_e32 v0, v0
	v_add_f32_e32 v1, v7, v223
	v_mul_f32_e32 v0, v0, v1
	v_cvt_pk_bf16_f32 v0, v0, s0
	s_and_saveexec_b64 s[4:5], s[0:1]
	s_xor_b64 s[4:5], exec, s[4:5]
	s_cbranch_execz .LBB0_627
	v_lshl_add_u64 v[2:3], v[66:67], 1, v[22:23]
	v_add_co_u32_e32 v2, vcc, 0x2000, v2
	s_nop 1
	v_addc_co_u32_e32 v3, vcc, 0, v3, vcc
	global_store_short v[2:3], v0, off offset:64 nt
.LBB0_627:
	s_andn2_saveexec_b64 s[4:5], s[4:5]
	s_cbranch_execz .LBB0_629
	v_lshl_add_u64 v[2:3], v[48:49], 1, v[22:23]
	global_store_short v[2:3], v0, off nt
.LBB0_629:
	s_or_b64 exec, exec, s[4:5]
	v_mul_f32_e64 v0, v92, |v75|
	v_mul_f32_e32 v0, 0x3fb8aa3b, v0
	v_exp_f32_e32 v0, v0
	v_add_f32_e32 v1, v8, v224
	v_mul_f32_e32 v0, v0, v1
	v_cvt_pk_bf16_f32 v0, v0, s0
	s_and_saveexec_b64 s[4:5], s[0:1]
	s_xor_b64 s[4:5], exec, s[4:5]
	s_cbranch_execz .LBB0_631
	v_lshl_add_u64 v[2:3], v[66:67], 1, v[40:41]
	v_add_co_u32_e32 v2, vcc, 0x2000, v2
	s_nop 1
	v_addc_co_u32_e32 v3, vcc, 0, v3, vcc
	global_store_short v[2:3], v0, off offset:64 nt
.LBB0_631:
	s_andn2_saveexec_b64 s[4:5], s[4:5]
	s_cbranch_execz .LBB0_633
	v_lshl_add_u64 v[2:3], v[48:49], 1, v[40:41]
	global_store_short v[2:3], v0, off nt
.LBB0_633:
	s_or_b64 exec, exec, s[4:5]
	v_mul_f32_e64 v0, v92, |v77|
	v_mul_f32_e32 v0, 0x3fb8aa3b, v0
	v_exp_f32_e32 v0, v0
	v_add_f32_e32 v1, v9, v225
	v_mul_f32_e32 v0, v0, v1
	v_cvt_pk_bf16_f32 v0, v0, s0
	s_and_saveexec_b64 s[4:5], s[0:1]
	s_xor_b64 s[4:5], exec, s[4:5]
	s_cbranch_execz .LBB0_635
	v_lshl_add_u64 v[2:3], v[66:67], 1, v[24:25]
	v_add_co_u32_e32 v2, vcc, 0x2000, v2
	s_nop 1
	v_addc_co_u32_e32 v3, vcc, 0, v3, vcc
	global_store_short v[2:3], v0, off offset:64 nt
.LBB0_635:
	s_andn2_saveexec_b64 s[4:5], s[4:5]
	s_cbranch_execz .LBB0_637
	v_lshl_add_u64 v[2:3], v[48:49], 1, v[24:25]
	global_store_short v[2:3], v0, off nt
.LBB0_637:
	s_or_b64 exec, exec, s[4:5]
	v_mul_f32_e64 v0, v92, |v79|
	v_mul_f32_e32 v0, 0x3fb8aa3b, v0
	v_exp_f32_e32 v0, v0
	v_add_f32_e32 v1, v10, v226
	v_mul_f32_e32 v0, v0, v1
	v_cvt_pk_bf16_f32 v0, v0, s0
	s_and_saveexec_b64 s[4:5], s[0:1]
	s_xor_b64 s[4:5], exec, s[4:5]
	s_cbranch_execz .LBB0_639
	v_lshl_add_u64 v[2:3], v[66:67], 1, v[42:43]
	v_add_co_u32_e32 v2, vcc, 0x2000, v2
	s_nop 1
	v_addc_co_u32_e32 v3, vcc, 0, v3, vcc
	global_store_short v[2:3], v0, off offset:64 nt
.LBB0_639:
	s_andn2_saveexec_b64 s[4:5], s[4:5]
	s_cbranch_execz .LBB0_641
	v_lshl_add_u64 v[2:3], v[48:49], 1, v[42:43]
	global_store_short v[2:3], v0, off nt
.LBB0_641:
	s_or_b64 exec, exec, s[4:5]
	v_mul_f32_e64 v0, v92, |v81|
	v_mul_f32_e32 v0, 0x3fb8aa3b, v0
	v_exp_f32_e32 v0, v0
	v_add_f32_e32 v1, v11, v227
	v_mul_f32_e32 v0, v0, v1
	v_cvt_pk_bf16_f32 v0, v0, s0
	s_and_saveexec_b64 s[4:5], s[0:1]
	s_xor_b64 s[4:5], exec, s[4:5]
	s_cbranch_execz .LBB0_643
	v_lshl_add_u64 v[2:3], v[66:67], 1, v[26:27]
	v_add_co_u32_e32 v2, vcc, 0x2000, v2
	s_nop 1
	v_addc_co_u32_e32 v3, vcc, 0, v3, vcc
	global_store_short v[2:3], v0, off offset:64 nt
.LBB0_643:
	s_andn2_saveexec_b64 s[4:5], s[4:5]
	s_cbranch_execz .LBB0_645
	v_lshl_add_u64 v[2:3], v[48:49], 1, v[26:27]
	global_store_short v[2:3], v0, off nt
.LBB0_645:
	s_or_b64 exec, exec, s[4:5]
	v_mul_f32_e64 v0, v92, |v83|
	v_mul_f32_e32 v0, 0x3fb8aa3b, v0
	v_exp_f32_e32 v0, v0
	v_add_f32_e32 v1, v12, v228
	v_mul_f32_e32 v0, v0, v1
	v_cvt_pk_bf16_f32 v0, v0, s0
	s_and_saveexec_b64 s[4:5], s[0:1]
	s_xor_b64 s[4:5], exec, s[4:5]
	s_cbranch_execz .LBB0_647
	v_lshl_add_u64 v[2:3], v[66:67], 1, v[44:45]
	v_add_co_u32_e32 v2, vcc, 0x2000, v2
	s_nop 1
	v_addc_co_u32_e32 v3, vcc, 0, v3, vcc
	global_store_short v[2:3], v0, off offset:64 nt
.LBB0_647:
	s_andn2_saveexec_b64 s[4:5], s[4:5]
	s_cbranch_execz .LBB0_649
	v_lshl_add_u64 v[2:3], v[48:49], 1, v[44:45]
	global_store_short v[2:3], v0, off nt
.LBB0_649:
	s_or_b64 exec, exec, s[4:5]
	v_mul_f32_e64 v0, v92, |v85|
	v_mul_f32_e32 v0, 0x3fb8aa3b, v0
	v_exp_f32_e32 v0, v0
	v_add_f32_e32 v1, v13, v229
	v_mul_f32_e32 v0, v0, v1
	v_cvt_pk_bf16_f32 v0, v0, s0
	s_and_saveexec_b64 s[4:5], s[0:1]
	s_xor_b64 s[4:5], exec, s[4:5]
	s_cbranch_execz .LBB0_651
	v_lshl_add_u64 v[2:3], v[66:67], 1, v[28:29]
	v_add_co_u32_e32 v2, vcc, 0x2000, v2
	s_nop 1
	v_addc_co_u32_e32 v3, vcc, 0, v3, vcc
	global_store_short v[2:3], v0, off offset:64 nt
.LBB0_651:
	s_andn2_saveexec_b64 s[4:5], s[4:5]
	s_cbranch_execz .LBB0_653
	v_lshl_add_u64 v[2:3], v[48:49], 1, v[28:29]
	global_store_short v[2:3], v0, off nt
.LBB0_653:
	s_or_b64 exec, exec, s[4:5]
	v_mul_f32_e64 v0, v92, |v87|
	v_mul_f32_e32 v0, 0x3fb8aa3b, v0
	v_exp_f32_e32 v0, v0
	v_add_f32_e32 v1, v14, v230
	v_mul_f32_e32 v0, v0, v1
	v_cvt_pk_bf16_f32 v0, v0, s0
	s_and_saveexec_b64 s[4:5], s[0:1]
	s_xor_b64 s[4:5], exec, s[4:5]
	s_cbranch_execz .LBB0_655
	v_lshl_add_u64 v[2:3], v[66:67], 1, v[46:47]
	v_add_co_u32_e32 v2, vcc, 0x2000, v2
	s_nop 1
	v_addc_co_u32_e32 v3, vcc, 0, v3, vcc
	global_store_short v[2:3], v0, off offset:64 nt
.LBB0_655:
	s_andn2_saveexec_b64 s[4:5], s[4:5]
	s_cbranch_execz .LBB0_657
	v_lshl_add_u64 v[2:3], v[48:49], 1, v[46:47]
	global_store_short v[2:3], v0, off nt
.LBB0_657:
	s_or_b64 exec, exec, s[4:5]
	v_mul_f32_e64 v0, v92, |v68|
	v_mul_f32_e32 v0, 0x3fb8aa3b, v0
	v_exp_f32_e32 v0, v0
	v_add_f32_e32 v1, v15, v231
	v_mul_f32_e32 v0, v0, v1
	v_cvt_pk_bf16_f32 v0, v0, s0
	s_and_saveexec_b64 s[4:5], s[0:1]
	s_xor_b64 s[0:1], exec, s[4:5]
	s_cbranch_execz .LBB0_659
	v_lshl_add_u64 v[2:3], v[66:67], 1, v[30:31]
	v_add_co_u32_e32 v2, vcc, 0x2000, v2
	s_nop 1
	v_addc_co_u32_e32 v3, vcc, 0, v3, vcc
	global_store_short v[2:3], v0, off offset:64 nt
.LBB0_659:
	s_andn2_saveexec_b64 s[0:1], s[0:1]
	s_cbranch_execz .LBB0_276
	v_lshl_add_u64 v[2:3], v[48:49], 1, v[30:31]
	global_store_short v[2:3], v0, off nt
	s_branch .LBB0_276
